# phase_conv: hand-written fast path for gridDim=256 (next item's 11 row loads issued before the current item is computed, counted vmcnt, packed f32 FMAs, output rows stored as they complete); compiler
# baseline (speedup 1.0000x reference)
; DI int otid() { int t = threadIdx.x; asm volatile("" : "+v"(t)); return t; }
; DI void phase_conv(const Params& p) {
;     const bf16_t* big = (const bf16_t*)(p.ws + ACT); bf16_t* xc = (bf16_t*)(p.ws + HBUF);
;     for (size_t idx = (size_t)blockIdx.x * 512 + otid(); idx < (size_t)(MTOK / 8) * 256; idx += (size_t)gridDim.x * 512) {
;         const int tok0 = (int)(idx >> 8) * 8, ch = (int)(idx & 255) * 8, t0 = tok0 & (SEQ - 1);
;         float wv[4][8], bs[8];
;         { const f32x4 b0 = *(const f32x4*)(p.in[15] + ch), b1 = *(const f32x4*)(p.in[15] + ch + 4);
; #pragma unroll
;           for (int e = 0; e < 4; ++e) { bs[e] = b0[e]; bs[4 + e] = b1[e]; } }
; #pragma unroll
;         for (int jx = 0; jx < 4; ++jx) { const f32x4 w0 = *(const f32x4*)(p.in[14] + jx * 2048 + ch), w1 = *(const f32x4*)(p.in[14] + jx * 2048 + ch + 4);
; #pragma unroll
;             for (int e = 0; e < 4; ++e) { wv[jx][e] = w0[e]; wv[jx][4 + e] = w1[e]; } }
;         u32x4 raw[11];
; #pragma unroll
;         for (int r = 0; r < 11; ++r) raw[r] = (r >= 3 || t0 > 0) ? *(const u32x4*)(big + (size_t)(tok0 - 3 + r) * 4096 + ch) : (u32x4){0u, 0u, 0u, 0u};
.LBB0_875:
	s_or_b64 exec, exec, s[8:9]
	s_mov_b32 s3, 0
	s_waitcnt lgkmcnt(0)
	v_mov_b32_e32 v0, v181
	s_barrier
	s_lshl_b64 s[8:9], s[2:3], 9
	s_nop 0
	v_ashrrev_i32_e32 v1, 31, v0
	s_waitcnt vmcnt(0)
	v_lshl_add_u64 v[54:55], s[8:9], 0, v[0:1]
	s_mov_b64 s[8:9], 0x80000
	v_cmp_gt_u64_e32 vcc, s[8:9], v[54:55]
	s_and_saveexec_b64 s[16:17], vcc
	s_cbranch_execz .LBB0_884
	s_cmp_eq_u32 s18, 0x100
	s_cbranch_scc0 .Lcv_orig
	s_load_dwordx2 s[42:43], s[0:1], 0xf0
	s_load_dwordx4 s[12:15], s[0:1], 0x70
	v_and_b32_e32 v88, 0xff, v181
	v_lshrrev_b32_e32 v89, 8, v181
	v_lshlrev_b32_e32 v160, 4, v88
	v_lshl_add_u32 v161, v89, 15, v160
	v_lshl_add_u32 v160, v89, 16, v160
	v_lshlrev_b32_e32 v162, 5, v88
	s_nop 0
	v_readfirstlane_b32 s40, v89
	s_or_b32 s40, s40, s2
	s_waitcnt lgkmcnt(0)
	s_lshl_b32 s41, s2, 17
	s_add_u32 s26, s42, 0xbf00000
	s_addc_u32 s27, s43, 0
	s_add_u32 s26, s26, s41
	s_addc_u32 s27, s27, 0
	s_sub_u32 s26, s26, 0x6000
	s_subb_u32 s27, s27, 0
	s_lshl_b32 s41, s2, 16
	s_add_u32 s28, s42, 0x7f00000
	s_addc_u32 s29, s43, 0
	s_add_u32 s28, s28, s41
	s_addc_u32 s29, s29, 0
	s_mov_b64 s[44:45], s[12:13]
	global_load_dwordx4 v[232:235], v162, s[44:45]
	global_load_dwordx4 v[236:239], v162, s[44:45] offset:16
	s_add_u32 s44, s44, 0x2000
	s_addc_u32 s45, s45, 0
	global_load_dwordx4 v[240:243], v162, s[44:45]
	global_load_dwordx4 v[244:247], v162, s[44:45] offset:16
	s_add_u32 s44, s44, 0x2000
	s_addc_u32 s45, s45, 0
	global_load_dwordx4 v[248:251], v162, s[44:45]
	global_load_dwordx4 v[252:255], v162, s[44:45] offset:16
	s_add_u32 s44, s44, 0x2000
	s_addc_u32 s45, s45, 0
	global_load_dwordx4 v[198:201], v162, s[44:45]
	global_load_dwordx4 v[202:205], v162, s[44:45] offset:16
	global_load_dwordx4 v[206:209], v162, s[14:15]
	global_load_dwordx4 v[210:213], v162, s[14:15] offset:16
	s_mov_b64 s[44:45], s[26:27]
	global_load_dwordx4 v[0:3], v160, s[44:45]
	s_add_u32 s44, s44, 0x2000
	s_addc_u32 s45, s45, 0
	global_load_dwordx4 v[4:7], v160, s[44:45]
	s_add_u32 s44, s44, 0x2000
	s_addc_u32 s45, s45, 0
	global_load_dwordx4 v[8:11], v160, s[44:45]
	s_add_u32 s44, s44, 0x2000
	s_addc_u32 s45, s45, 0
	global_load_dwordx4 v[12:15], v160, s[44:45]
	s_add_u32 s44, s44, 0x2000
	s_addc_u32 s45, s45, 0
	global_load_dwordx4 v[16:19], v160, s[44:45]
	s_add_u32 s44, s44, 0x2000
	s_addc_u32 s45, s45, 0
	global_load_dwordx4 v[20:23], v160, s[44:45]
	s_add_u32 s44, s44, 0x2000
	s_addc_u32 s45, s45, 0
	global_load_dwordx4 v[24:27], v160, s[44:45]
	s_add_u32 s44, s44, 0x2000
	s_addc_u32 s45, s45, 0
	global_load_dwordx4 v[28:31], v160, s[44:45]
	s_add_u32 s44, s44, 0x2000
	s_addc_u32 s45, s45, 0
	global_load_dwordx4 v[32:35], v160, s[44:45]
	s_add_u32 s44, s44, 0x2000
	s_addc_u32 s45, s45, 0
	global_load_dwordx4 v[36:39], v160, s[44:45]
	s_add_u32 s44, s44, 0x2000
	s_addc_u32 s45, s45, 0
	global_load_dwordx4 v[40:43], v160, s[44:45]
	s_add_u32 s26, s26, 0x2000000
	s_addc_u32 s27, s27, 0
	s_mov_b64 s[44:45], s[26:27]
	global_load_dwordx4 v[44:47], v160, s[44:45]
	s_add_u32 s44, s44, 0x2000
	s_addc_u32 s45, s45, 0
	global_load_dwordx4 v[48:51], v160, s[44:45]
	s_add_u32 s44, s44, 0x2000
	s_addc_u32 s45, s45, 0
	global_load_dwordx4 v[52:55], v160, s[44:45]
	s_add_u32 s44, s44, 0x2000
	s_addc_u32 s45, s45, 0
	global_load_dwordx4 v[56:59], v160, s[44:45]
	s_add_u32 s44, s44, 0x2000
	s_addc_u32 s45, s45, 0
	global_load_dwordx4 v[60:63], v160, s[44:45]
	s_add_u32 s44, s44, 0x2000
	s_addc_u32 s45, s45, 0
	global_load_dwordx4 v[64:67], v160, s[44:45]
	s_add_u32 s44, s44, 0x2000
	s_addc_u32 s45, s45, 0
	global_load_dwordx4 v[68:71], v160, s[44:45]
	s_add_u32 s44, s44, 0x2000
	s_addc_u32 s45, s45, 0
	global_load_dwordx4 v[72:75], v160, s[44:45]
	s_add_u32 s44, s44, 0x2000
	s_addc_u32 s45, s45, 0
	global_load_dwordx4 v[76:79], v160, s[44:45]
	s_add_u32 s44, s44, 0x2000
	s_addc_u32 s45, s45, 0
	global_load_dwordx4 v[80:83], v160, s[44:45]
	s_add_u32 s44, s44, 0x2000
	s_addc_u32 s45, s45, 0
	global_load_dwordx4 v[84:87], v160, s[44:45]
	s_add_u32 s26, s26, 0x2000000
	s_addc_u32 s27, s27, 0
	s_waitcnt vmcnt(11)
	s_cmp_eq_u32 s40, 0
	s_cbranch_scc0 .Lcv_nopad0
	v_mov_b32_e32 v0, 0
	v_mov_b32_e32 v1, 0
	v_mov_b32_e32 v2, 0
	v_mov_b32_e32 v3, 0
	v_mov_b32_e32 v4, 0
	v_mov_b32_e32 v5, 0
	v_mov_b32_e32 v6, 0
	v_mov_b32_e32 v7, 0
	v_mov_b32_e32 v8, 0
	v_mov_b32_e32 v9, 0
	v_mov_b32_e32 v10, 0
	v_mov_b32_e32 v11, 0
; DI u32x4 pack8(const float (&f)[8]) { u32x4 w; w.x = pk2(f[0], f[1]); w.y = pk2(f[2], f[3]); w.z = pk2(f[4], f[5]); w.w = pk2(f[6], f[7]); return w; }
; DI void phase_conv(const Params& p) {
;     ...
; #pragma unroll
;         for (int o = 0; o < 8; ++o) {
;             float acc[8];
; #pragma unroll
;             for (int e = 0; e < 8; ++e) acc[e] = bs[e];
; #pragma unroll
;             for (int jx = 0; jx < 4; ++jx) { float f[8]; unpack8(raw[o + jx], f);
; #pragma unroll
;                 for (int e = 0; e < 8; ++e) acc[e] += f[e] * wv[jx][e]; }
;             *(u32x4*)(xc + (size_t)(tok0 + o) * DM + ch) = pack8(acc);
;         }
.Lcv_nopad0:
	s_mov_b64 s[44:45], s[28:29]
	v_lshlrev_b32_e32 v88, 16, v0
	v_and_b32_e32 v89, 0xffff0000, v0
	v_lshlrev_b32_e32 v90, 16, v1
	v_and_b32_e32 v91, 0xffff0000, v1
	v_lshlrev_b32_e32 v92, 16, v2
	v_and_b32_e32 v93, 0xffff0000, v2
	v_lshlrev_b32_e32 v94, 16, v3
	v_and_b32_e32 v95, 0xffff0000, v3
	v_pk_fma_f32 v[96:97], v[88:89], v[232:233], v[206:207]
	v_pk_fma_f32 v[98:99], v[90:91], v[234:235], v[208:209]
	v_pk_fma_f32 v[100:101], v[92:93], v[236:237], v[210:211]
	v_pk_fma_f32 v[102:103], v[94:95], v[238:239], v[212:213]
	v_lshlrev_b32_e32 v88, 16, v4
	v_and_b32_e32 v89, 0xffff0000, v4
	v_lshlrev_b32_e32 v90, 16, v5
	v_and_b32_e32 v91, 0xffff0000, v5
	v_lshlrev_b32_e32 v92, 16, v6
	v_and_b32_e32 v93, 0xffff0000, v6
	v_lshlrev_b32_e32 v94, 16, v7
	v_and_b32_e32 v95, 0xffff0000, v7
	v_pk_fma_f32 v[96:97], v[88:89], v[240:241], v[96:97]
	v_pk_fma_f32 v[98:99], v[90:91], v[242:243], v[98:99]
	v_pk_fma_f32 v[100:101], v[92:93], v[244:245], v[100:101]
	v_pk_fma_f32 v[102:103], v[94:95], v[246:247], v[102:103]
	v_pk_fma_f32 v[104:105], v[88:89], v[232:233], v[206:207]
	v_pk_fma_f32 v[106:107], v[90:91], v[234:235], v[208:209]
	v_pk_fma_f32 v[108:109], v[92:93], v[236:237], v[210:211]
	v_pk_fma_f32 v[110:111], v[94:95], v[238:239], v[212:213]
	v_lshlrev_b32_e32 v88, 16, v8
	v_and_b32_e32 v89, 0xffff0000, v8
	v_lshlrev_b32_e32 v90, 16, v9
	v_and_b32_e32 v91, 0xffff0000, v9
	v_lshlrev_b32_e32 v92, 16, v10
	v_and_b32_e32 v93, 0xffff0000, v10
	v_lshlrev_b32_e32 v94, 16, v11
	v_and_b32_e32 v95, 0xffff0000, v11
	v_pk_fma_f32 v[96:97], v[88:89], v[248:249], v[96:97]
	v_pk_fma_f32 v[98:99], v[90:91], v[250:251], v[98:99]
	v_pk_fma_f32 v[100:101], v[92:93], v[252:253], v[100:101]
	v_pk_fma_f32 v[102:103], v[94:95], v[254:255], v[102:103]
	v_pk_fma_f32 v[104:105], v[88:89], v[240:241], v[104:105]
	v_pk_fma_f32 v[106:107], v[90:91], v[242:243], v[106:107]
	v_pk_fma_f32 v[108:109], v[92:93], v[244:245], v[108:109]
	v_pk_fma_f32 v[110:111], v[94:95], v[246:247], v[110:111]
	v_pk_fma_f32 v[112:113], v[88:89], v[232:233], v[206:207]
	v_pk_fma_f32 v[114:115], v[90:91], v[234:235], v[208:209]
	v_pk_fma_f32 v[116:117], v[92:93], v[236:237], v[210:211]
	v_pk_fma_f32 v[118:119], v[94:95], v[238:239], v[212:213]
	v_lshlrev_b32_e32 v88, 16, v12
	v_and_b32_e32 v89, 0xffff0000, v12
	v_lshlrev_b32_e32 v90, 16, v13
	v_and_b32_e32 v91, 0xffff0000, v13
	v_lshlrev_b32_e32 v92, 16, v14
	v_and_b32_e32 v93, 0xffff0000, v14
	v_lshlrev_b32_e32 v94, 16, v15
	v_and_b32_e32 v95, 0xffff0000, v15
	v_pk_fma_f32 v[96:97], v[88:89], v[198:199], v[96:97]
	v_pk_fma_f32 v[98:99], v[90:91], v[200:201], v[98:99]
	v_pk_fma_f32 v[100:101], v[92:93], v[202:203], v[100:101]
	v_pk_fma_f32 v[102:103], v[94:95], v[204:205], v[102:103]
	v_pk_fma_f32 v[104:105], v[88:89], v[248:249], v[104:105]
	v_pk_fma_f32 v[106:107], v[90:91], v[250:251], v[106:107]
	v_pk_fma_f32 v[108:109], v[92:93], v[252:253], v[108:109]
	v_pk_fma_f32 v[110:111], v[94:95], v[254:255], v[110:111]
	v_pk_fma_f32 v[112:113], v[88:89], v[240:241], v[112:113]
	v_pk_fma_f32 v[114:115], v[90:91], v[242:243], v[114:115]
	v_pk_fma_f32 v[116:117], v[92:93], v[244:245], v[116:117]
	v_pk_fma_f32 v[118:119], v[94:95], v[246:247], v[118:119]
	v_pk_fma_f32 v[120:121], v[88:89], v[232:233], v[206:207]
	v_pk_fma_f32 v[122:123], v[90:91], v[234:235], v[208:209]
	v_pk_fma_f32 v[124:125], v[92:93], v[236:237], v[210:211]
	v_pk_fma_f32 v[126:127], v[94:95], v[238:239], v[212:213]
	v_cvt_pk_bf16_f32 v164, v96, v97
	v_cvt_pk_bf16_f32 v165, v98, v99
	v_cvt_pk_bf16_f32 v166, v100, v101
	v_cvt_pk_bf16_f32 v167, v102, v103
	global_store_dwordx4 v161, v[164:167], s[44:45]
	s_add_u32 s44, s44, 0x1000
	s_addc_u32 s45, s45, 0
	s_nop 1
	v_lshlrev_b32_e32 v88, 16, v16
	v_and_b32_e32 v89, 0xffff0000, v16
	v_lshlrev_b32_e32 v90, 16, v17
	v_and_b32_e32 v91, 0xffff0000, v17
	v_lshlrev_b32_e32 v92, 16, v18
	v_and_b32_e32 v93, 0xffff0000, v18
	v_lshlrev_b32_e32 v94, 16, v19
	v_and_b32_e32 v95, 0xffff0000, v19
	v_pk_fma_f32 v[104:105], v[88:89], v[198:199], v[104:105]
	v_pk_fma_f32 v[106:107], v[90:91], v[200:201], v[106:107]
	v_pk_fma_f32 v[108:109], v[92:93], v[202:203], v[108:109]
	v_pk_fma_f32 v[110:111], v[94:95], v[204:205], v[110:111]
	v_pk_fma_f32 v[112:113], v[88:89], v[248:249], v[112:113]
	v_pk_fma_f32 v[114:115], v[90:91], v[250:251], v[114:115]
	v_pk_fma_f32 v[116:117], v[92:93], v[252:253], v[116:117]
	v_pk_fma_f32 v[118:119], v[94:95], v[254:255], v[118:119]
	v_pk_fma_f32 v[120:121], v[88:89], v[240:241], v[120:121]
	v_pk_fma_f32 v[122:123], v[90:91], v[242:243], v[122:123]
	v_pk_fma_f32 v[124:125], v[92:93], v[244:245], v[124:125]
	v_pk_fma_f32 v[126:127], v[94:95], v[246:247], v[126:127]
	v_pk_fma_f32 v[128:129], v[88:89], v[232:233], v[206:207]
	v_pk_fma_f32 v[130:131], v[90:91], v[234:235], v[208:209]
	v_pk_fma_f32 v[132:133], v[92:93], v[236:237], v[210:211]
	v_pk_fma_f32 v[134:135], v[94:95], v[238:239], v[212:213]
	v_cvt_pk_bf16_f32 v164, v104, v105
	v_cvt_pk_bf16_f32 v165, v106, v107
	v_cvt_pk_bf16_f32 v166, v108, v109
	v_cvt_pk_bf16_f32 v167, v110, v111
	global_store_dwordx4 v161, v[164:167], s[44:45]
	s_add_u32 s44, s44, 0x1000
	s_addc_u32 s45, s45, 0
	s_nop 1
	v_lshlrev_b32_e32 v88, 16, v20
	v_and_b32_e32 v89, 0xffff0000, v20
	v_lshlrev_b32_e32 v90, 16, v21
	v_and_b32_e32 v91, 0xffff0000, v21
	v_lshlrev_b32_e32 v92, 16, v22
	v_and_b32_e32 v93, 0xffff0000, v22
	v_lshlrev_b32_e32 v94, 16, v23
	v_and_b32_e32 v95, 0xffff0000, v23
	v_pk_fma_f32 v[112:113], v[88:89], v[198:199], v[112:113]
	v_pk_fma_f32 v[114:115], v[90:91], v[200:201], v[114:115]
	v_pk_fma_f32 v[116:117], v[92:93], v[202:203], v[116:117]
; DI u32x4 pack8(const float (&f)[8]) { u32x4 w; w.x = pk2(f[0], f[1]); w.y = pk2(f[2], f[3]); w.z = pk2(f[4], f[5]); w.w = pk2(f[6], f[7]); return w; }
; DI void phase_conv(const Params& p) {
;     ...
; #pragma unroll
;         for (int o = 0; o < 8; ++o) {
;             float acc[8];
; #pragma unroll
;             for (int e = 0; e < 8; ++e) acc[e] = bs[e];
; #pragma unroll
;             for (int jx = 0; jx < 4; ++jx) { float f[8]; unpack8(raw[o + jx], f);
; #pragma unroll
;                 for (int e = 0; e < 8; ++e) acc[e] += f[e] * wv[jx][e]; }
;             *(u32x4*)(xc + (size_t)(tok0 + o) * DM + ch) = pack8(acc);
;         }
	v_pk_fma_f32 v[118:119], v[94:95], v[204:205], v[118:119]
	v_pk_fma_f32 v[120:121], v[88:89], v[248:249], v[120:121]
	v_pk_fma_f32 v[122:123], v[90:91], v[250:251], v[122:123]
	v_pk_fma_f32 v[124:125], v[92:93], v[252:253], v[124:125]
	v_pk_fma_f32 v[126:127], v[94:95], v[254:255], v[126:127]
	v_pk_fma_f32 v[128:129], v[88:89], v[240:241], v[128:129]
	v_pk_fma_f32 v[130:131], v[90:91], v[242:243], v[130:131]
	v_pk_fma_f32 v[132:133], v[92:93], v[244:245], v[132:133]
	v_pk_fma_f32 v[134:135], v[94:95], v[246:247], v[134:135]
	v_pk_fma_f32 v[136:137], v[88:89], v[232:233], v[206:207]
	v_pk_fma_f32 v[138:139], v[90:91], v[234:235], v[208:209]
	v_pk_fma_f32 v[140:141], v[92:93], v[236:237], v[210:211]
	v_pk_fma_f32 v[142:143], v[94:95], v[238:239], v[212:213]
	v_cvt_pk_bf16_f32 v164, v112, v113
	v_cvt_pk_bf16_f32 v165, v114, v115
	v_cvt_pk_bf16_f32 v166, v116, v117
	v_cvt_pk_bf16_f32 v167, v118, v119
	global_store_dwordx4 v161, v[164:167], s[44:45]
	s_add_u32 s44, s44, 0x1000
	s_addc_u32 s45, s45, 0
	s_nop 1
	v_lshlrev_b32_e32 v88, 16, v24
	v_and_b32_e32 v89, 0xffff0000, v24
	v_lshlrev_b32_e32 v90, 16, v25
	v_and_b32_e32 v91, 0xffff0000, v25
	v_lshlrev_b32_e32 v92, 16, v26
	v_and_b32_e32 v93, 0xffff0000, v26
	v_lshlrev_b32_e32 v94, 16, v27
	v_and_b32_e32 v95, 0xffff0000, v27
	v_pk_fma_f32 v[120:121], v[88:89], v[198:199], v[120:121]
	v_pk_fma_f32 v[122:123], v[90:91], v[200:201], v[122:123]
	v_pk_fma_f32 v[124:125], v[92:93], v[202:203], v[124:125]
	v_pk_fma_f32 v[126:127], v[94:95], v[204:205], v[126:127]
	v_pk_fma_f32 v[128:129], v[88:89], v[248:249], v[128:129]
	v_pk_fma_f32 v[130:131], v[90:91], v[250:251], v[130:131]
	v_pk_fma_f32 v[132:133], v[92:93], v[252:253], v[132:133]
	v_pk_fma_f32 v[134:135], v[94:95], v[254:255], v[134:135]
	v_pk_fma_f32 v[136:137], v[88:89], v[240:241], v[136:137]
	v_pk_fma_f32 v[138:139], v[90:91], v[242:243], v[138:139]
	v_pk_fma_f32 v[140:141], v[92:93], v[244:245], v[140:141]
	v_pk_fma_f32 v[142:143], v[94:95], v[246:247], v[142:143]
	v_pk_fma_f32 v[144:145], v[88:89], v[232:233], v[206:207]
	v_pk_fma_f32 v[146:147], v[90:91], v[234:235], v[208:209]
	v_pk_fma_f32 v[148:149], v[92:93], v[236:237], v[210:211]
	v_pk_fma_f32 v[150:151], v[94:95], v[238:239], v[212:213]
	v_cvt_pk_bf16_f32 v164, v120, v121
	v_cvt_pk_bf16_f32 v165, v122, v123
	v_cvt_pk_bf16_f32 v166, v124, v125
	v_cvt_pk_bf16_f32 v167, v126, v127
	global_store_dwordx4 v161, v[164:167], s[44:45]
	s_add_u32 s44, s44, 0x1000
	s_addc_u32 s45, s45, 0
	s_nop 1
	v_lshlrev_b32_e32 v88, 16, v28
	v_and_b32_e32 v89, 0xffff0000, v28
	v_lshlrev_b32_e32 v90, 16, v29
	v_and_b32_e32 v91, 0xffff0000, v29
	v_lshlrev_b32_e32 v92, 16, v30
	v_and_b32_e32 v93, 0xffff0000, v30
	v_lshlrev_b32_e32 v94, 16, v31
	v_and_b32_e32 v95, 0xffff0000, v31
	v_pk_fma_f32 v[128:129], v[88:89], v[198:199], v[128:129]
	v_pk_fma_f32 v[130:131], v[90:91], v[200:201], v[130:131]
	v_pk_fma_f32 v[132:133], v[92:93], v[202:203], v[132:133]
	v_pk_fma_f32 v[134:135], v[94:95], v[204:205], v[134:135]
	v_pk_fma_f32 v[136:137], v[88:89], v[248:249], v[136:137]
	v_pk_fma_f32 v[138:139], v[90:91], v[250:251], v[138:139]
	v_pk_fma_f32 v[140:141], v[92:93], v[252:253], v[140:141]
	v_pk_fma_f32 v[142:143], v[94:95], v[254:255], v[142:143]
	v_pk_fma_f32 v[144:145], v[88:89], v[240:241], v[144:145]
	v_pk_fma_f32 v[146:147], v[90:91], v[242:243], v[146:147]
	v_pk_fma_f32 v[148:149], v[92:93], v[244:245], v[148:149]
	v_pk_fma_f32 v[150:151], v[94:95], v[246:247], v[150:151]
	v_pk_fma_f32 v[152:153], v[88:89], v[232:233], v[206:207]
	v_pk_fma_f32 v[154:155], v[90:91], v[234:235], v[208:209]
	v_pk_fma_f32 v[156:157], v[92:93], v[236:237], v[210:211]
	v_pk_fma_f32 v[158:159], v[94:95], v[238:239], v[212:213]
	v_cvt_pk_bf16_f32 v164, v128, v129
	v_cvt_pk_bf16_f32 v165, v130, v131
	v_cvt_pk_bf16_f32 v166, v132, v133
	v_cvt_pk_bf16_f32 v167, v134, v135
	global_store_dwordx4 v161, v[164:167], s[44:45]
	s_add_u32 s44, s44, 0x1000
	s_addc_u32 s45, s45, 0
	s_nop 1
	v_lshlrev_b32_e32 v88, 16, v32
	v_and_b32_e32 v89, 0xffff0000, v32
	v_lshlrev_b32_e32 v90, 16, v33
	v_and_b32_e32 v91, 0xffff0000, v33
	v_lshlrev_b32_e32 v92, 16, v34
	v_and_b32_e32 v93, 0xffff0000, v34
	v_lshlrev_b32_e32 v94, 16, v35
	v_and_b32_e32 v95, 0xffff0000, v35
	v_pk_fma_f32 v[136:137], v[88:89], v[198:199], v[136:137]
	v_pk_fma_f32 v[138:139], v[90:91], v[200:201], v[138:139]
	v_pk_fma_f32 v[140:141], v[92:93], v[202:203], v[140:141]
	v_pk_fma_f32 v[142:143], v[94:95], v[204:205], v[142:143]
	v_pk_fma_f32 v[144:145], v[88:89], v[248:249], v[144:145]
	v_pk_fma_f32 v[146:147], v[90:91], v[250:251], v[146:147]
	v_pk_fma_f32 v[148:149], v[92:93], v[252:253], v[148:149]
	v_pk_fma_f32 v[150:151], v[94:95], v[254:255], v[150:151]
	v_pk_fma_f32 v[152:153], v[88:89], v[240:241], v[152:153]
	v_pk_fma_f32 v[154:155], v[90:91], v[242:243], v[154:155]
	v_pk_fma_f32 v[156:157], v[92:93], v[244:245], v[156:157]
	v_pk_fma_f32 v[158:159], v[94:95], v[246:247], v[158:159]
	v_cvt_pk_bf16_f32 v164, v136, v137
	v_cvt_pk_bf16_f32 v165, v138, v139
	v_cvt_pk_bf16_f32 v166, v140, v141
	v_cvt_pk_bf16_f32 v167, v142, v143
	global_store_dwordx4 v161, v[164:167], s[44:45]
	s_add_u32 s44, s44, 0x1000
	s_addc_u32 s45, s45, 0
	s_nop 1
	v_lshlrev_b32_e32 v88, 16, v36
	v_and_b32_e32 v89, 0xffff0000, v36
	v_lshlrev_b32_e32 v90, 16, v37
	v_and_b32_e32 v91, 0xffff0000, v37
	v_lshlrev_b32_e32 v92, 16, v38
	v_and_b32_e32 v93, 0xffff0000, v38
	v_lshlrev_b32_e32 v94, 16, v39
	v_and_b32_e32 v95, 0xffff0000, v39
	v_pk_fma_f32 v[144:145], v[88:89], v[198:199], v[144:145]
	v_pk_fma_f32 v[146:147], v[90:91], v[200:201], v[146:147]
	v_pk_fma_f32 v[148:149], v[92:93], v[202:203], v[148:149]
; DI u32x4 pack8(const float (&f)[8]) { u32x4 w; w.x = pk2(f[0], f[1]); w.y = pk2(f[2], f[3]); w.z = pk2(f[4], f[5]); w.w = pk2(f[6], f[7]); return w; }
; DI void phase_conv(const Params& p) {
;     ...
;         for (int r = 0; r < 11; ++r) raw[r] = (r >= 3 || t0 > 0) ? *(const u32x4*)(big + (size_t)(tok0 - 3 + r) * 4096 + ch) : (u32x4){0u, 0u, 0u, 0u};
; #pragma unroll
;         for (int o = 0; o < 8; ++o) {
;             float acc[8];
; #pragma unroll
;             for (int e = 0; e < 8; ++e) acc[e] = bs[e];
; #pragma unroll
;             for (int jx = 0; jx < 4; ++jx) { float f[8]; unpack8(raw[o + jx], f);
; #pragma unroll
;                 for (int e = 0; e < 8; ++e) acc[e] += f[e] * wv[jx][e]; }
;             *(u32x4*)(xc + (size_t)(tok0 + o) * DM + ch) = pack8(acc);
;         }
	v_pk_fma_f32 v[150:151], v[94:95], v[204:205], v[150:151]
	v_pk_fma_f32 v[152:153], v[88:89], v[248:249], v[152:153]
	v_pk_fma_f32 v[154:155], v[90:91], v[250:251], v[154:155]
	v_pk_fma_f32 v[156:157], v[92:93], v[252:253], v[156:157]
	v_pk_fma_f32 v[158:159], v[94:95], v[254:255], v[158:159]
	v_cvt_pk_bf16_f32 v164, v144, v145
	v_cvt_pk_bf16_f32 v165, v146, v147
	v_cvt_pk_bf16_f32 v166, v148, v149
	v_cvt_pk_bf16_f32 v167, v150, v151
	global_store_dwordx4 v161, v[164:167], s[44:45]
	s_add_u32 s44, s44, 0x1000
	s_addc_u32 s45, s45, 0
	s_nop 1
	v_lshlrev_b32_e32 v88, 16, v40
	v_and_b32_e32 v89, 0xffff0000, v40
	v_lshlrev_b32_e32 v90, 16, v41
	v_and_b32_e32 v91, 0xffff0000, v41
	v_lshlrev_b32_e32 v92, 16, v42
	v_and_b32_e32 v93, 0xffff0000, v42
	v_lshlrev_b32_e32 v94, 16, v43
	v_and_b32_e32 v95, 0xffff0000, v43
	v_pk_fma_f32 v[152:153], v[88:89], v[198:199], v[152:153]
	v_pk_fma_f32 v[154:155], v[90:91], v[200:201], v[154:155]
	v_pk_fma_f32 v[156:157], v[92:93], v[202:203], v[156:157]
	v_pk_fma_f32 v[158:159], v[94:95], v[204:205], v[158:159]
	v_cvt_pk_bf16_f32 v164, v152, v153
	v_cvt_pk_bf16_f32 v165, v154, v155
	v_cvt_pk_bf16_f32 v166, v156, v157
	v_cvt_pk_bf16_f32 v167, v158, v159
	global_store_dwordx4 v161, v[164:167], s[44:45]
	s_add_u32 s44, s44, 0x1000
	s_addc_u32 s45, s45, 0
	s_nop 1
	s_add_u32 s28, s28, 0x1000000
	s_addc_u32 s29, s29, 0
	s_mov_b64 s[44:45], s[26:27]
	global_load_dwordx4 v[0:3], v160, s[44:45]
	s_add_u32 s44, s44, 0x2000
	s_addc_u32 s45, s45, 0
	global_load_dwordx4 v[4:7], v160, s[44:45]
	s_add_u32 s44, s44, 0x2000
	s_addc_u32 s45, s45, 0
	global_load_dwordx4 v[8:11], v160, s[44:45]
	s_add_u32 s44, s44, 0x2000
	s_addc_u32 s45, s45, 0
	global_load_dwordx4 v[12:15], v160, s[44:45]
	s_add_u32 s44, s44, 0x2000
	s_addc_u32 s45, s45, 0
	global_load_dwordx4 v[16:19], v160, s[44:45]
	s_add_u32 s44, s44, 0x2000
	s_addc_u32 s45, s45, 0
	global_load_dwordx4 v[20:23], v160, s[44:45]
	s_add_u32 s44, s44, 0x2000
	s_addc_u32 s45, s45, 0
	global_load_dwordx4 v[24:27], v160, s[44:45]
	s_add_u32 s44, s44, 0x2000
	s_addc_u32 s45, s45, 0
	global_load_dwordx4 v[28:31], v160, s[44:45]
	s_add_u32 s44, s44, 0x2000
	s_addc_u32 s45, s45, 0
	global_load_dwordx4 v[32:35], v160, s[44:45]
	s_add_u32 s44, s44, 0x2000
	s_addc_u32 s45, s45, 0
	global_load_dwordx4 v[36:39], v160, s[44:45]
	s_add_u32 s44, s44, 0x2000
	s_addc_u32 s45, s45, 0
	global_load_dwordx4 v[40:43], v160, s[44:45]
	s_add_u32 s26, s26, 0x2000000
	s_addc_u32 s27, s27, 0
	s_waitcnt vmcnt(19)
	s_cmp_eq_u32 s40, 0
	s_cbranch_scc0 .Lcv_nopad1
	v_mov_b32_e32 v44, 0
	v_mov_b32_e32 v45, 0
	v_mov_b32_e32 v46, 0
	v_mov_b32_e32 v47, 0
	v_mov_b32_e32 v48, 0
	v_mov_b32_e32 v49, 0
	v_mov_b32_e32 v50, 0
	v_mov_b32_e32 v51, 0
	v_mov_b32_e32 v52, 0
	v_mov_b32_e32 v53, 0
	v_mov_b32_e32 v54, 0
	v_mov_b32_e32 v55, 0
.Lcv_nopad1:
	s_mov_b64 s[44:45], s[28:29]
	v_lshlrev_b32_e32 v88, 16, v44
	v_and_b32_e32 v89, 0xffff0000, v44
	v_lshlrev_b32_e32 v90, 16, v45
	v_and_b32_e32 v91, 0xffff0000, v45
	v_lshlrev_b32_e32 v92, 16, v46
	v_and_b32_e32 v93, 0xffff0000, v46
	v_lshlrev_b32_e32 v94, 16, v47
	v_and_b32_e32 v95, 0xffff0000, v47
	v_pk_fma_f32 v[96:97], v[88:89], v[232:233], v[206:207]
	v_pk_fma_f32 v[98:99], v[90:91], v[234:235], v[208:209]
	v_pk_fma_f32 v[100:101], v[92:93], v[236:237], v[210:211]
	v_pk_fma_f32 v[102:103], v[94:95], v[238:239], v[212:213]
	v_lshlrev_b32_e32 v88, 16, v48
	v_and_b32_e32 v89, 0xffff0000, v48
	v_lshlrev_b32_e32 v90, 16, v49
	v_and_b32_e32 v91, 0xffff0000, v49
	v_lshlrev_b32_e32 v92, 16, v50
	v_and_b32_e32 v93, 0xffff0000, v50
	v_lshlrev_b32_e32 v94, 16, v51
	v_and_b32_e32 v95, 0xffff0000, v51
	v_pk_fma_f32 v[96:97], v[88:89], v[240:241], v[96:97]
	v_pk_fma_f32 v[98:99], v[90:91], v[242:243], v[98:99]
	v_pk_fma_f32 v[100:101], v[92:93], v[244:245], v[100:101]
	v_pk_fma_f32 v[102:103], v[94:95], v[246:247], v[102:103]
	v_pk_fma_f32 v[104:105], v[88:89], v[232:233], v[206:207]
	v_pk_fma_f32 v[106:107], v[90:91], v[234:235], v[208:209]
	v_pk_fma_f32 v[108:109], v[92:93], v[236:237], v[210:211]
	v_pk_fma_f32 v[110:111], v[94:95], v[238:239], v[212:213]
	v_lshlrev_b32_e32 v88, 16, v52
	v_and_b32_e32 v89, 0xffff0000, v52
	v_lshlrev_b32_e32 v90, 16, v53
	v_and_b32_e32 v91, 0xffff0000, v53
	v_lshlrev_b32_e32 v92, 16, v54
	v_and_b32_e32 v93, 0xffff0000, v54
	v_lshlrev_b32_e32 v94, 16, v55
	v_and_b32_e32 v95, 0xffff0000, v55
	v_pk_fma_f32 v[96:97], v[88:89], v[248:249], v[96:97]
	v_pk_fma_f32 v[98:99], v[90:91], v[250:251], v[98:99]
	v_pk_fma_f32 v[100:101], v[92:93], v[252:253], v[100:101]
	v_pk_fma_f32 v[102:103], v[94:95], v[254:255], v[102:103]
	v_pk_fma_f32 v[104:105], v[88:89], v[240:241], v[104:105]
	v_pk_fma_f32 v[106:107], v[90:91], v[242:243], v[106:107]
	v_pk_fma_f32 v[108:109], v[92:93], v[244:245], v[108:109]
	v_pk_fma_f32 v[110:111], v[94:95], v[246:247], v[110:111]
	v_pk_fma_f32 v[112:113], v[88:89], v[232:233], v[206:207]
	v_pk_fma_f32 v[114:115], v[90:91], v[234:235], v[208:209]
	v_pk_fma_f32 v[116:117], v[92:93], v[236:237], v[210:211]
	v_pk_fma_f32 v[118:119], v[94:95], v[238:239], v[212:213]
	v_lshlrev_b32_e32 v88, 16, v56
	v_and_b32_e32 v89, 0xffff0000, v56
	v_lshlrev_b32_e32 v90, 16, v57
	v_and_b32_e32 v91, 0xffff0000, v57
	v_lshlrev_b32_e32 v92, 16, v58
	v_and_b32_e32 v93, 0xffff0000, v58
	v_lshlrev_b32_e32 v94, 16, v59
	v_and_b32_e32 v95, 0xffff0000, v59
	v_pk_fma_f32 v[96:97], v[88:89], v[198:199], v[96:97]
	v_pk_fma_f32 v[98:99], v[90:91], v[200:201], v[98:99]
	v_pk_fma_f32 v[100:101], v[92:93], v[202:203], v[100:101]
	v_pk_fma_f32 v[102:103], v[94:95], v[204:205], v[102:103]
	v_pk_fma_f32 v[104:105], v[88:89], v[248:249], v[104:105]
; DI u32x4 pack8(const float (&f)[8]) { u32x4 w; w.x = pk2(f[0], f[1]); w.y = pk2(f[2], f[3]); w.z = pk2(f[4], f[5]); w.w = pk2(f[6], f[7]); return w; }
; DI void phase_conv(const Params& p) {
;     ...
; #pragma unroll
;         for (int o = 0; o < 8; ++o) {
;             float acc[8];
; #pragma unroll
;             for (int e = 0; e < 8; ++e) acc[e] = bs[e];
; #pragma unroll
;             for (int jx = 0; jx < 4; ++jx) { float f[8]; unpack8(raw[o + jx], f);
; #pragma unroll
;                 for (int e = 0; e < 8; ++e) acc[e] += f[e] * wv[jx][e]; }
;             *(u32x4*)(xc + (size_t)(tok0 + o) * DM + ch) = pack8(acc);
;         }
	v_pk_fma_f32 v[106:107], v[90:91], v[250:251], v[106:107]
	v_pk_fma_f32 v[108:109], v[92:93], v[252:253], v[108:109]
	v_pk_fma_f32 v[110:111], v[94:95], v[254:255], v[110:111]
	v_pk_fma_f32 v[112:113], v[88:89], v[240:241], v[112:113]
	v_pk_fma_f32 v[114:115], v[90:91], v[242:243], v[114:115]
	v_pk_fma_f32 v[116:117], v[92:93], v[244:245], v[116:117]
	v_pk_fma_f32 v[118:119], v[94:95], v[246:247], v[118:119]
	v_pk_fma_f32 v[120:121], v[88:89], v[232:233], v[206:207]
	v_pk_fma_f32 v[122:123], v[90:91], v[234:235], v[208:209]
	v_pk_fma_f32 v[124:125], v[92:93], v[236:237], v[210:211]
	v_pk_fma_f32 v[126:127], v[94:95], v[238:239], v[212:213]
	v_cvt_pk_bf16_f32 v164, v96, v97
	v_cvt_pk_bf16_f32 v165, v98, v99
	v_cvt_pk_bf16_f32 v166, v100, v101
	v_cvt_pk_bf16_f32 v167, v102, v103
	global_store_dwordx4 v161, v[164:167], s[44:45]
	s_add_u32 s44, s44, 0x1000
	s_addc_u32 s45, s45, 0
	s_nop 1
	v_lshlrev_b32_e32 v88, 16, v60
	v_and_b32_e32 v89, 0xffff0000, v60
	v_lshlrev_b32_e32 v90, 16, v61
	v_and_b32_e32 v91, 0xffff0000, v61
	v_lshlrev_b32_e32 v92, 16, v62
	v_and_b32_e32 v93, 0xffff0000, v62
	v_lshlrev_b32_e32 v94, 16, v63
	v_and_b32_e32 v95, 0xffff0000, v63
	v_pk_fma_f32 v[104:105], v[88:89], v[198:199], v[104:105]
	v_pk_fma_f32 v[106:107], v[90:91], v[200:201], v[106:107]
	v_pk_fma_f32 v[108:109], v[92:93], v[202:203], v[108:109]
	v_pk_fma_f32 v[110:111], v[94:95], v[204:205], v[110:111]
	v_pk_fma_f32 v[112:113], v[88:89], v[248:249], v[112:113]
	v_pk_fma_f32 v[114:115], v[90:91], v[250:251], v[114:115]
	v_pk_fma_f32 v[116:117], v[92:93], v[252:253], v[116:117]
	v_pk_fma_f32 v[118:119], v[94:95], v[254:255], v[118:119]
	v_pk_fma_f32 v[120:121], v[88:89], v[240:241], v[120:121]
	v_pk_fma_f32 v[122:123], v[90:91], v[242:243], v[122:123]
	v_pk_fma_f32 v[124:125], v[92:93], v[244:245], v[124:125]
	v_pk_fma_f32 v[126:127], v[94:95], v[246:247], v[126:127]
	v_pk_fma_f32 v[128:129], v[88:89], v[232:233], v[206:207]
	v_pk_fma_f32 v[130:131], v[90:91], v[234:235], v[208:209]
	v_pk_fma_f32 v[132:133], v[92:93], v[236:237], v[210:211]
	v_pk_fma_f32 v[134:135], v[94:95], v[238:239], v[212:213]
	v_cvt_pk_bf16_f32 v164, v104, v105
	v_cvt_pk_bf16_f32 v165, v106, v107
	v_cvt_pk_bf16_f32 v166, v108, v109
	v_cvt_pk_bf16_f32 v167, v110, v111
	global_store_dwordx4 v161, v[164:167], s[44:45]
	s_add_u32 s44, s44, 0x1000
	s_addc_u32 s45, s45, 0
	s_nop 1
	v_lshlrev_b32_e32 v88, 16, v64
	v_and_b32_e32 v89, 0xffff0000, v64
	v_lshlrev_b32_e32 v90, 16, v65
	v_and_b32_e32 v91, 0xffff0000, v65
	v_lshlrev_b32_e32 v92, 16, v66
	v_and_b32_e32 v93, 0xffff0000, v66
	v_lshlrev_b32_e32 v94, 16, v67
	v_and_b32_e32 v95, 0xffff0000, v67
	v_pk_fma_f32 v[112:113], v[88:89], v[198:199], v[112:113]
	v_pk_fma_f32 v[114:115], v[90:91], v[200:201], v[114:115]
	v_pk_fma_f32 v[116:117], v[92:93], v[202:203], v[116:117]
	v_pk_fma_f32 v[118:119], v[94:95], v[204:205], v[118:119]
	v_pk_fma_f32 v[120:121], v[88:89], v[248:249], v[120:121]
	v_pk_fma_f32 v[122:123], v[90:91], v[250:251], v[122:123]
	v_pk_fma_f32 v[124:125], v[92:93], v[252:253], v[124:125]
	v_pk_fma_f32 v[126:127], v[94:95], v[254:255], v[126:127]
	v_pk_fma_f32 v[128:129], v[88:89], v[240:241], v[128:129]
	v_pk_fma_f32 v[130:131], v[90:91], v[242:243], v[130:131]
	v_pk_fma_f32 v[132:133], v[92:93], v[244:245], v[132:133]
	v_pk_fma_f32 v[134:135], v[94:95], v[246:247], v[134:135]
	v_pk_fma_f32 v[136:137], v[88:89], v[232:233], v[206:207]
	v_pk_fma_f32 v[138:139], v[90:91], v[234:235], v[208:209]
	v_pk_fma_f32 v[140:141], v[92:93], v[236:237], v[210:211]
	v_pk_fma_f32 v[142:143], v[94:95], v[238:239], v[212:213]
	v_cvt_pk_bf16_f32 v164, v112, v113
	v_cvt_pk_bf16_f32 v165, v114, v115
	v_cvt_pk_bf16_f32 v166, v116, v117
	v_cvt_pk_bf16_f32 v167, v118, v119
	global_store_dwordx4 v161, v[164:167], s[44:45]
	s_add_u32 s44, s44, 0x1000
	s_addc_u32 s45, s45, 0
	s_nop 1
	v_lshlrev_b32_e32 v88, 16, v68
	v_and_b32_e32 v89, 0xffff0000, v68
	v_lshlrev_b32_e32 v90, 16, v69
	v_and_b32_e32 v91, 0xffff0000, v69
	v_lshlrev_b32_e32 v92, 16, v70
	v_and_b32_e32 v93, 0xffff0000, v70
	v_lshlrev_b32_e32 v94, 16, v71
	v_and_b32_e32 v95, 0xffff0000, v71
	v_pk_fma_f32 v[120:121], v[88:89], v[198:199], v[120:121]
	v_pk_fma_f32 v[122:123], v[90:91], v[200:201], v[122:123]
	v_pk_fma_f32 v[124:125], v[92:93], v[202:203], v[124:125]
	v_pk_fma_f32 v[126:127], v[94:95], v[204:205], v[126:127]
	v_pk_fma_f32 v[128:129], v[88:89], v[248:249], v[128:129]
	v_pk_fma_f32 v[130:131], v[90:91], v[250:251], v[130:131]
	v_pk_fma_f32 v[132:133], v[92:93], v[252:253], v[132:133]
	v_pk_fma_f32 v[134:135], v[94:95], v[254:255], v[134:135]
	v_pk_fma_f32 v[136:137], v[88:89], v[240:241], v[136:137]
	v_pk_fma_f32 v[138:139], v[90:91], v[242:243], v[138:139]
	v_pk_fma_f32 v[140:141], v[92:93], v[244:245], v[140:141]
	v_pk_fma_f32 v[142:143], v[94:95], v[246:247], v[142:143]
	v_pk_fma_f32 v[144:145], v[88:89], v[232:233], v[206:207]
	v_pk_fma_f32 v[146:147], v[90:91], v[234:235], v[208:209]
	v_pk_fma_f32 v[148:149], v[92:93], v[236:237], v[210:211]
	v_pk_fma_f32 v[150:151], v[94:95], v[238:239], v[212:213]
	v_cvt_pk_bf16_f32 v164, v120, v121
	v_cvt_pk_bf16_f32 v165, v122, v123
	v_cvt_pk_bf16_f32 v166, v124, v125
	v_cvt_pk_bf16_f32 v167, v126, v127
	global_store_dwordx4 v161, v[164:167], s[44:45]
	s_add_u32 s44, s44, 0x1000
	s_addc_u32 s45, s45, 0
	s_nop 1
	v_lshlrev_b32_e32 v88, 16, v72
	v_and_b32_e32 v89, 0xffff0000, v72
	v_lshlrev_b32_e32 v90, 16, v73
	v_and_b32_e32 v91, 0xffff0000, v73
	v_lshlrev_b32_e32 v92, 16, v74
	v_and_b32_e32 v93, 0xffff0000, v74
	v_lshlrev_b32_e32 v94, 16, v75
	v_and_b32_e32 v95, 0xffff0000, v75
	v_pk_fma_f32 v[128:129], v[88:89], v[198:199], v[128:129]
; DI u32x4 pack8(const float (&f)[8]) { u32x4 w; w.x = pk2(f[0], f[1]); w.y = pk2(f[2], f[3]); w.z = pk2(f[4], f[5]); w.w = pk2(f[6], f[7]); return w; }
; DI void phase_conv(const Params& p) {
;     ...
;         for (int r = 0; r < 11; ++r) raw[r] = (r >= 3 || t0 > 0) ? *(const u32x4*)(big + (size_t)(tok0 - 3 + r) * 4096 + ch) : (u32x4){0u, 0u, 0u, 0u};
; #pragma unroll
;         for (int o = 0; o < 8; ++o) {
;             float acc[8];
; #pragma unroll
;             for (int e = 0; e < 8; ++e) acc[e] = bs[e];
; #pragma unroll
;             for (int jx = 0; jx < 4; ++jx) { float f[8]; unpack8(raw[o + jx], f);
; #pragma unroll
;                 for (int e = 0; e < 8; ++e) acc[e] += f[e] * wv[jx][e]; }
;             *(u32x4*)(xc + (size_t)(tok0 + o) * DM + ch) = pack8(acc);
;         }
	v_pk_fma_f32 v[130:131], v[90:91], v[200:201], v[130:131]
	v_pk_fma_f32 v[132:133], v[92:93], v[202:203], v[132:133]
	v_pk_fma_f32 v[134:135], v[94:95], v[204:205], v[134:135]
	v_pk_fma_f32 v[136:137], v[88:89], v[248:249], v[136:137]
	v_pk_fma_f32 v[138:139], v[90:91], v[250:251], v[138:139]
	v_pk_fma_f32 v[140:141], v[92:93], v[252:253], v[140:141]
	v_pk_fma_f32 v[142:143], v[94:95], v[254:255], v[142:143]
	v_pk_fma_f32 v[144:145], v[88:89], v[240:241], v[144:145]
	v_pk_fma_f32 v[146:147], v[90:91], v[242:243], v[146:147]
	v_pk_fma_f32 v[148:149], v[92:93], v[244:245], v[148:149]
	v_pk_fma_f32 v[150:151], v[94:95], v[246:247], v[150:151]
	v_pk_fma_f32 v[152:153], v[88:89], v[232:233], v[206:207]
	v_pk_fma_f32 v[154:155], v[90:91], v[234:235], v[208:209]
	v_pk_fma_f32 v[156:157], v[92:93], v[236:237], v[210:211]
	v_pk_fma_f32 v[158:159], v[94:95], v[238:239], v[212:213]
	v_cvt_pk_bf16_f32 v164, v128, v129
	v_cvt_pk_bf16_f32 v165, v130, v131
	v_cvt_pk_bf16_f32 v166, v132, v133
	v_cvt_pk_bf16_f32 v167, v134, v135
	global_store_dwordx4 v161, v[164:167], s[44:45]
	s_add_u32 s44, s44, 0x1000
	s_addc_u32 s45, s45, 0
	s_nop 1
	v_lshlrev_b32_e32 v88, 16, v76
	v_and_b32_e32 v89, 0xffff0000, v76
	v_lshlrev_b32_e32 v90, 16, v77
	v_and_b32_e32 v91, 0xffff0000, v77
	v_lshlrev_b32_e32 v92, 16, v78
	v_and_b32_e32 v93, 0xffff0000, v78
	v_lshlrev_b32_e32 v94, 16, v79
	v_and_b32_e32 v95, 0xffff0000, v79
	v_pk_fma_f32 v[136:137], v[88:89], v[198:199], v[136:137]
	v_pk_fma_f32 v[138:139], v[90:91], v[200:201], v[138:139]
	v_pk_fma_f32 v[140:141], v[92:93], v[202:203], v[140:141]
	v_pk_fma_f32 v[142:143], v[94:95], v[204:205], v[142:143]
	v_pk_fma_f32 v[144:145], v[88:89], v[248:249], v[144:145]
	v_pk_fma_f32 v[146:147], v[90:91], v[250:251], v[146:147]
	v_pk_fma_f32 v[148:149], v[92:93], v[252:253], v[148:149]
	v_pk_fma_f32 v[150:151], v[94:95], v[254:255], v[150:151]
	v_pk_fma_f32 v[152:153], v[88:89], v[240:241], v[152:153]
	v_pk_fma_f32 v[154:155], v[90:91], v[242:243], v[154:155]
	v_pk_fma_f32 v[156:157], v[92:93], v[244:245], v[156:157]
	v_pk_fma_f32 v[158:159], v[94:95], v[246:247], v[158:159]
	v_cvt_pk_bf16_f32 v164, v136, v137
	v_cvt_pk_bf16_f32 v165, v138, v139
	v_cvt_pk_bf16_f32 v166, v140, v141
	v_cvt_pk_bf16_f32 v167, v142, v143
	global_store_dwordx4 v161, v[164:167], s[44:45]
	s_add_u32 s44, s44, 0x1000
	s_addc_u32 s45, s45, 0
	s_nop 1
	v_lshlrev_b32_e32 v88, 16, v80
	v_and_b32_e32 v89, 0xffff0000, v80
	v_lshlrev_b32_e32 v90, 16, v81
	v_and_b32_e32 v91, 0xffff0000, v81
	v_lshlrev_b32_e32 v92, 16, v82
	v_and_b32_e32 v93, 0xffff0000, v82
	v_lshlrev_b32_e32 v94, 16, v83
	v_and_b32_e32 v95, 0xffff0000, v83
	v_pk_fma_f32 v[144:145], v[88:89], v[198:199], v[144:145]
	v_pk_fma_f32 v[146:147], v[90:91], v[200:201], v[146:147]
	v_pk_fma_f32 v[148:149], v[92:93], v[202:203], v[148:149]
	v_pk_fma_f32 v[150:151], v[94:95], v[204:205], v[150:151]
	v_pk_fma_f32 v[152:153], v[88:89], v[248:249], v[152:153]
	v_pk_fma_f32 v[154:155], v[90:91], v[250:251], v[154:155]
	v_pk_fma_f32 v[156:157], v[92:93], v[252:253], v[156:157]
	v_pk_fma_f32 v[158:159], v[94:95], v[254:255], v[158:159]
	v_cvt_pk_bf16_f32 v164, v144, v145
	v_cvt_pk_bf16_f32 v165, v146, v147
	v_cvt_pk_bf16_f32 v166, v148, v149
	v_cvt_pk_bf16_f32 v167, v150, v151
	global_store_dwordx4 v161, v[164:167], s[44:45]
	s_add_u32 s44, s44, 0x1000
	s_addc_u32 s45, s45, 0
	s_nop 1
	v_lshlrev_b32_e32 v88, 16, v84
	v_and_b32_e32 v89, 0xffff0000, v84
	v_lshlrev_b32_e32 v90, 16, v85
	v_and_b32_e32 v91, 0xffff0000, v85
	v_lshlrev_b32_e32 v92, 16, v86
	v_and_b32_e32 v93, 0xffff0000, v86
	v_lshlrev_b32_e32 v94, 16, v87
	v_and_b32_e32 v95, 0xffff0000, v87
	v_pk_fma_f32 v[152:153], v[88:89], v[198:199], v[152:153]
	v_pk_fma_f32 v[154:155], v[90:91], v[200:201], v[154:155]
	v_pk_fma_f32 v[156:157], v[92:93], v[202:203], v[156:157]
	v_pk_fma_f32 v[158:159], v[94:95], v[204:205], v[158:159]
	v_cvt_pk_bf16_f32 v164, v152, v153
	v_cvt_pk_bf16_f32 v165, v154, v155
	v_cvt_pk_bf16_f32 v166, v156, v157
	v_cvt_pk_bf16_f32 v167, v158, v159
	global_store_dwordx4 v161, v[164:167], s[44:45]
	s_add_u32 s44, s44, 0x1000
	s_addc_u32 s45, s45, 0
	s_nop 1
	s_add_u32 s28, s28, 0x1000000
	s_addc_u32 s29, s29, 0
	s_mov_b64 s[44:45], s[26:27]
	global_load_dwordx4 v[44:47], v160, s[44:45]
	s_add_u32 s44, s44, 0x2000
	s_addc_u32 s45, s45, 0
	global_load_dwordx4 v[48:51], v160, s[44:45]
	s_add_u32 s44, s44, 0x2000
	s_addc_u32 s45, s45, 0
	global_load_dwordx4 v[52:55], v160, s[44:45]
	s_add_u32 s44, s44, 0x2000
	s_addc_u32 s45, s45, 0
	global_load_dwordx4 v[56:59], v160, s[44:45]
	s_add_u32 s44, s44, 0x2000
	s_addc_u32 s45, s45, 0
	global_load_dwordx4 v[60:63], v160, s[44:45]
	s_add_u32 s44, s44, 0x2000
	s_addc_u32 s45, s45, 0
	global_load_dwordx4 v[64:67], v160, s[44:45]
	s_add_u32 s44, s44, 0x2000
	s_addc_u32 s45, s45, 0
	global_load_dwordx4 v[68:71], v160, s[44:45]
	s_add_u32 s44, s44, 0x2000
	s_addc_u32 s45, s45, 0
	global_load_dwordx4 v[72:75], v160, s[44:45]
	s_add_u32 s44, s44, 0x2000
	s_addc_u32 s45, s45, 0
	global_load_dwordx4 v[76:79], v160, s[44:45]
	s_add_u32 s44, s44, 0x2000
	s_addc_u32 s45, s45, 0
	global_load_dwordx4 v[80:83], v160, s[44:45]
	s_add_u32 s44, s44, 0x2000
	s_addc_u32 s45, s45, 0
	global_load_dwordx4 v[84:87], v160, s[44:45]
	s_add_u32 s26, s26, 0x2000000
	s_addc_u32 s27, s27, 0
	s_waitcnt vmcnt(19)
	s_cmp_eq_u32 s40, 0
	s_cbranch_scc0 .Lcv_nopad2
	v_mov_b32_e32 v0, 0
	v_mov_b32_e32 v1, 0
	v_mov_b32_e32 v2, 0
	v_mov_b32_e32 v3, 0
	v_mov_b32_e32 v4, 0
	v_mov_b32_e32 v5, 0
	v_mov_b32_e32 v6, 0
	v_mov_b32_e32 v7, 0
	v_mov_b32_e32 v8, 0
	v_mov_b32_e32 v9, 0
	v_mov_b32_e32 v10, 0
	v_mov_b32_e32 v11, 0
; DI u32x4 pack8(const float (&f)[8]) { u32x4 w; w.x = pk2(f[0], f[1]); w.y = pk2(f[2], f[3]); w.z = pk2(f[4], f[5]); w.w = pk2(f[6], f[7]); return w; }
; DI void phase_conv(const Params& p) {
;     ...
; #pragma unroll
;         for (int o = 0; o < 8; ++o) {
;             float acc[8];
; #pragma unroll
;             for (int e = 0; e < 8; ++e) acc[e] = bs[e];
; #pragma unroll
;             for (int jx = 0; jx < 4; ++jx) { float f[8]; unpack8(raw[o + jx], f);
; #pragma unroll
;                 for (int e = 0; e < 8; ++e) acc[e] += f[e] * wv[jx][e]; }
;             *(u32x4*)(xc + (size_t)(tok0 + o) * DM + ch) = pack8(acc);
;         }
.Lcv_nopad2:
	s_mov_b64 s[44:45], s[28:29]
	v_lshlrev_b32_e32 v88, 16, v0
	v_and_b32_e32 v89, 0xffff0000, v0
	v_lshlrev_b32_e32 v90, 16, v1
	v_and_b32_e32 v91, 0xffff0000, v1
	v_lshlrev_b32_e32 v92, 16, v2
	v_and_b32_e32 v93, 0xffff0000, v2
	v_lshlrev_b32_e32 v94, 16, v3
	v_and_b32_e32 v95, 0xffff0000, v3
	v_pk_fma_f32 v[96:97], v[88:89], v[232:233], v[206:207]
	v_pk_fma_f32 v[98:99], v[90:91], v[234:235], v[208:209]
	v_pk_fma_f32 v[100:101], v[92:93], v[236:237], v[210:211]
	v_pk_fma_f32 v[102:103], v[94:95], v[238:239], v[212:213]
	v_lshlrev_b32_e32 v88, 16, v4
	v_and_b32_e32 v89, 0xffff0000, v4
	v_lshlrev_b32_e32 v90, 16, v5
	v_and_b32_e32 v91, 0xffff0000, v5
	v_lshlrev_b32_e32 v92, 16, v6
	v_and_b32_e32 v93, 0xffff0000, v6
	v_lshlrev_b32_e32 v94, 16, v7
	v_and_b32_e32 v95, 0xffff0000, v7
	v_pk_fma_f32 v[96:97], v[88:89], v[240:241], v[96:97]
	v_pk_fma_f32 v[98:99], v[90:91], v[242:243], v[98:99]
	v_pk_fma_f32 v[100:101], v[92:93], v[244:245], v[100:101]
	v_pk_fma_f32 v[102:103], v[94:95], v[246:247], v[102:103]
	v_pk_fma_f32 v[104:105], v[88:89], v[232:233], v[206:207]
	v_pk_fma_f32 v[106:107], v[90:91], v[234:235], v[208:209]
	v_pk_fma_f32 v[108:109], v[92:93], v[236:237], v[210:211]
	v_pk_fma_f32 v[110:111], v[94:95], v[238:239], v[212:213]
	v_lshlrev_b32_e32 v88, 16, v8
	v_and_b32_e32 v89, 0xffff0000, v8
	v_lshlrev_b32_e32 v90, 16, v9
	v_and_b32_e32 v91, 0xffff0000, v9
	v_lshlrev_b32_e32 v92, 16, v10
	v_and_b32_e32 v93, 0xffff0000, v10
	v_lshlrev_b32_e32 v94, 16, v11
	v_and_b32_e32 v95, 0xffff0000, v11
	v_pk_fma_f32 v[96:97], v[88:89], v[248:249], v[96:97]
	v_pk_fma_f32 v[98:99], v[90:91], v[250:251], v[98:99]
	v_pk_fma_f32 v[100:101], v[92:93], v[252:253], v[100:101]
	v_pk_fma_f32 v[102:103], v[94:95], v[254:255], v[102:103]
	v_pk_fma_f32 v[104:105], v[88:89], v[240:241], v[104:105]
	v_pk_fma_f32 v[106:107], v[90:91], v[242:243], v[106:107]
	v_pk_fma_f32 v[108:109], v[92:93], v[244:245], v[108:109]
	v_pk_fma_f32 v[110:111], v[94:95], v[246:247], v[110:111]
	v_pk_fma_f32 v[112:113], v[88:89], v[232:233], v[206:207]
	v_pk_fma_f32 v[114:115], v[90:91], v[234:235], v[208:209]
	v_pk_fma_f32 v[116:117], v[92:93], v[236:237], v[210:211]
	v_pk_fma_f32 v[118:119], v[94:95], v[238:239], v[212:213]
	v_lshlrev_b32_e32 v88, 16, v12
	v_and_b32_e32 v89, 0xffff0000, v12
	v_lshlrev_b32_e32 v90, 16, v13
	v_and_b32_e32 v91, 0xffff0000, v13
	v_lshlrev_b32_e32 v92, 16, v14
	v_and_b32_e32 v93, 0xffff0000, v14
	v_lshlrev_b32_e32 v94, 16, v15
	v_and_b32_e32 v95, 0xffff0000, v15
	v_pk_fma_f32 v[96:97], v[88:89], v[198:199], v[96:97]
	v_pk_fma_f32 v[98:99], v[90:91], v[200:201], v[98:99]
	v_pk_fma_f32 v[100:101], v[92:93], v[202:203], v[100:101]
	v_pk_fma_f32 v[102:103], v[94:95], v[204:205], v[102:103]
	v_pk_fma_f32 v[104:105], v[88:89], v[248:249], v[104:105]
	v_pk_fma_f32 v[106:107], v[90:91], v[250:251], v[106:107]
	v_pk_fma_f32 v[108:109], v[92:93], v[252:253], v[108:109]
	v_pk_fma_f32 v[110:111], v[94:95], v[254:255], v[110:111]
	v_pk_fma_f32 v[112:113], v[88:89], v[240:241], v[112:113]
	v_pk_fma_f32 v[114:115], v[90:91], v[242:243], v[114:115]
	v_pk_fma_f32 v[116:117], v[92:93], v[244:245], v[116:117]
	v_pk_fma_f32 v[118:119], v[94:95], v[246:247], v[118:119]
	v_pk_fma_f32 v[120:121], v[88:89], v[232:233], v[206:207]
	v_pk_fma_f32 v[122:123], v[90:91], v[234:235], v[208:209]
	v_pk_fma_f32 v[124:125], v[92:93], v[236:237], v[210:211]
	v_pk_fma_f32 v[126:127], v[94:95], v[238:239], v[212:213]
	v_cvt_pk_bf16_f32 v164, v96, v97
	v_cvt_pk_bf16_f32 v165, v98, v99
	v_cvt_pk_bf16_f32 v166, v100, v101
	v_cvt_pk_bf16_f32 v167, v102, v103
	global_store_dwordx4 v161, v[164:167], s[44:45]
	s_add_u32 s44, s44, 0x1000
	s_addc_u32 s45, s45, 0
	s_nop 1
	v_lshlrev_b32_e32 v88, 16, v16
	v_and_b32_e32 v89, 0xffff0000, v16
	v_lshlrev_b32_e32 v90, 16, v17
	v_and_b32_e32 v91, 0xffff0000, v17
	v_lshlrev_b32_e32 v92, 16, v18
	v_and_b32_e32 v93, 0xffff0000, v18
	v_lshlrev_b32_e32 v94, 16, v19
	v_and_b32_e32 v95, 0xffff0000, v19
	v_pk_fma_f32 v[104:105], v[88:89], v[198:199], v[104:105]
	v_pk_fma_f32 v[106:107], v[90:91], v[200:201], v[106:107]
	v_pk_fma_f32 v[108:109], v[92:93], v[202:203], v[108:109]
	v_pk_fma_f32 v[110:111], v[94:95], v[204:205], v[110:111]
	v_pk_fma_f32 v[112:113], v[88:89], v[248:249], v[112:113]
	v_pk_fma_f32 v[114:115], v[90:91], v[250:251], v[114:115]
	v_pk_fma_f32 v[116:117], v[92:93], v[252:253], v[116:117]
	v_pk_fma_f32 v[118:119], v[94:95], v[254:255], v[118:119]
	v_pk_fma_f32 v[120:121], v[88:89], v[240:241], v[120:121]
	v_pk_fma_f32 v[122:123], v[90:91], v[242:243], v[122:123]
	v_pk_fma_f32 v[124:125], v[92:93], v[244:245], v[124:125]
	v_pk_fma_f32 v[126:127], v[94:95], v[246:247], v[126:127]
	v_pk_fma_f32 v[128:129], v[88:89], v[232:233], v[206:207]
	v_pk_fma_f32 v[130:131], v[90:91], v[234:235], v[208:209]
	v_pk_fma_f32 v[132:133], v[92:93], v[236:237], v[210:211]
	v_pk_fma_f32 v[134:135], v[94:95], v[238:239], v[212:213]
	v_cvt_pk_bf16_f32 v164, v104, v105
	v_cvt_pk_bf16_f32 v165, v106, v107
	v_cvt_pk_bf16_f32 v166, v108, v109
	v_cvt_pk_bf16_f32 v167, v110, v111
	global_store_dwordx4 v161, v[164:167], s[44:45]
	s_add_u32 s44, s44, 0x1000
	s_addc_u32 s45, s45, 0
	s_nop 1
	v_lshlrev_b32_e32 v88, 16, v20
	v_and_b32_e32 v89, 0xffff0000, v20
	v_lshlrev_b32_e32 v90, 16, v21
	v_and_b32_e32 v91, 0xffff0000, v21
	v_lshlrev_b32_e32 v92, 16, v22
	v_and_b32_e32 v93, 0xffff0000, v22
	v_lshlrev_b32_e32 v94, 16, v23
	v_and_b32_e32 v95, 0xffff0000, v23
	v_pk_fma_f32 v[112:113], v[88:89], v[198:199], v[112:113]
	v_pk_fma_f32 v[114:115], v[90:91], v[200:201], v[114:115]
	v_pk_fma_f32 v[116:117], v[92:93], v[202:203], v[116:117]
; DI u32x4 pack8(const float (&f)[8]) { u32x4 w; w.x = pk2(f[0], f[1]); w.y = pk2(f[2], f[3]); w.z = pk2(f[4], f[5]); w.w = pk2(f[6], f[7]); return w; }
; DI void phase_conv(const Params& p) {
;     ...
; #pragma unroll
;         for (int o = 0; o < 8; ++o) {
;             float acc[8];
; #pragma unroll
;             for (int e = 0; e < 8; ++e) acc[e] = bs[e];
; #pragma unroll
;             for (int jx = 0; jx < 4; ++jx) { float f[8]; unpack8(raw[o + jx], f);
; #pragma unroll
;                 for (int e = 0; e < 8; ++e) acc[e] += f[e] * wv[jx][e]; }
;             *(u32x4*)(xc + (size_t)(tok0 + o) * DM + ch) = pack8(acc);
;         }
	v_pk_fma_f32 v[118:119], v[94:95], v[204:205], v[118:119]
	v_pk_fma_f32 v[120:121], v[88:89], v[248:249], v[120:121]
	v_pk_fma_f32 v[122:123], v[90:91], v[250:251], v[122:123]
	v_pk_fma_f32 v[124:125], v[92:93], v[252:253], v[124:125]
	v_pk_fma_f32 v[126:127], v[94:95], v[254:255], v[126:127]
	v_pk_fma_f32 v[128:129], v[88:89], v[240:241], v[128:129]
	v_pk_fma_f32 v[130:131], v[90:91], v[242:243], v[130:131]
	v_pk_fma_f32 v[132:133], v[92:93], v[244:245], v[132:133]
	v_pk_fma_f32 v[134:135], v[94:95], v[246:247], v[134:135]
	v_pk_fma_f32 v[136:137], v[88:89], v[232:233], v[206:207]
	v_pk_fma_f32 v[138:139], v[90:91], v[234:235], v[208:209]
	v_pk_fma_f32 v[140:141], v[92:93], v[236:237], v[210:211]
	v_pk_fma_f32 v[142:143], v[94:95], v[238:239], v[212:213]
	v_cvt_pk_bf16_f32 v164, v112, v113
	v_cvt_pk_bf16_f32 v165, v114, v115
	v_cvt_pk_bf16_f32 v166, v116, v117
	v_cvt_pk_bf16_f32 v167, v118, v119
	global_store_dwordx4 v161, v[164:167], s[44:45]
	s_add_u32 s44, s44, 0x1000
	s_addc_u32 s45, s45, 0
	s_nop 1
	v_lshlrev_b32_e32 v88, 16, v24
	v_and_b32_e32 v89, 0xffff0000, v24
	v_lshlrev_b32_e32 v90, 16, v25
	v_and_b32_e32 v91, 0xffff0000, v25
	v_lshlrev_b32_e32 v92, 16, v26
	v_and_b32_e32 v93, 0xffff0000, v26
	v_lshlrev_b32_e32 v94, 16, v27
	v_and_b32_e32 v95, 0xffff0000, v27
	v_pk_fma_f32 v[120:121], v[88:89], v[198:199], v[120:121]
	v_pk_fma_f32 v[122:123], v[90:91], v[200:201], v[122:123]
	v_pk_fma_f32 v[124:125], v[92:93], v[202:203], v[124:125]
	v_pk_fma_f32 v[126:127], v[94:95], v[204:205], v[126:127]
	v_pk_fma_f32 v[128:129], v[88:89], v[248:249], v[128:129]
	v_pk_fma_f32 v[130:131], v[90:91], v[250:251], v[130:131]
	v_pk_fma_f32 v[132:133], v[92:93], v[252:253], v[132:133]
	v_pk_fma_f32 v[134:135], v[94:95], v[254:255], v[134:135]
	v_pk_fma_f32 v[136:137], v[88:89], v[240:241], v[136:137]
	v_pk_fma_f32 v[138:139], v[90:91], v[242:243], v[138:139]
	v_pk_fma_f32 v[140:141], v[92:93], v[244:245], v[140:141]
	v_pk_fma_f32 v[142:143], v[94:95], v[246:247], v[142:143]
	v_pk_fma_f32 v[144:145], v[88:89], v[232:233], v[206:207]
	v_pk_fma_f32 v[146:147], v[90:91], v[234:235], v[208:209]
	v_pk_fma_f32 v[148:149], v[92:93], v[236:237], v[210:211]
	v_pk_fma_f32 v[150:151], v[94:95], v[238:239], v[212:213]
	v_cvt_pk_bf16_f32 v164, v120, v121
	v_cvt_pk_bf16_f32 v165, v122, v123
	v_cvt_pk_bf16_f32 v166, v124, v125
	v_cvt_pk_bf16_f32 v167, v126, v127
	global_store_dwordx4 v161, v[164:167], s[44:45]
	s_add_u32 s44, s44, 0x1000
	s_addc_u32 s45, s45, 0
	s_nop 1
	v_lshlrev_b32_e32 v88, 16, v28
	v_and_b32_e32 v89, 0xffff0000, v28
	v_lshlrev_b32_e32 v90, 16, v29
	v_and_b32_e32 v91, 0xffff0000, v29
	v_lshlrev_b32_e32 v92, 16, v30
	v_and_b32_e32 v93, 0xffff0000, v30
	v_lshlrev_b32_e32 v94, 16, v31
	v_and_b32_e32 v95, 0xffff0000, v31
	v_pk_fma_f32 v[128:129], v[88:89], v[198:199], v[128:129]
	v_pk_fma_f32 v[130:131], v[90:91], v[200:201], v[130:131]
	v_pk_fma_f32 v[132:133], v[92:93], v[202:203], v[132:133]
	v_pk_fma_f32 v[134:135], v[94:95], v[204:205], v[134:135]
	v_pk_fma_f32 v[136:137], v[88:89], v[248:249], v[136:137]
	v_pk_fma_f32 v[138:139], v[90:91], v[250:251], v[138:139]
	v_pk_fma_f32 v[140:141], v[92:93], v[252:253], v[140:141]
	v_pk_fma_f32 v[142:143], v[94:95], v[254:255], v[142:143]
	v_pk_fma_f32 v[144:145], v[88:89], v[240:241], v[144:145]
	v_pk_fma_f32 v[146:147], v[90:91], v[242:243], v[146:147]
	v_pk_fma_f32 v[148:149], v[92:93], v[244:245], v[148:149]
	v_pk_fma_f32 v[150:151], v[94:95], v[246:247], v[150:151]
	v_pk_fma_f32 v[152:153], v[88:89], v[232:233], v[206:207]
	v_pk_fma_f32 v[154:155], v[90:91], v[234:235], v[208:209]
	v_pk_fma_f32 v[156:157], v[92:93], v[236:237], v[210:211]
	v_pk_fma_f32 v[158:159], v[94:95], v[238:239], v[212:213]
	v_cvt_pk_bf16_f32 v164, v128, v129
	v_cvt_pk_bf16_f32 v165, v130, v131
	v_cvt_pk_bf16_f32 v166, v132, v133
	v_cvt_pk_bf16_f32 v167, v134, v135
	global_store_dwordx4 v161, v[164:167], s[44:45]
	s_add_u32 s44, s44, 0x1000
	s_addc_u32 s45, s45, 0
	s_nop 1
	v_lshlrev_b32_e32 v88, 16, v32
	v_and_b32_e32 v89, 0xffff0000, v32
	v_lshlrev_b32_e32 v90, 16, v33
	v_and_b32_e32 v91, 0xffff0000, v33
	v_lshlrev_b32_e32 v92, 16, v34
	v_and_b32_e32 v93, 0xffff0000, v34
	v_lshlrev_b32_e32 v94, 16, v35
	v_and_b32_e32 v95, 0xffff0000, v35
	v_pk_fma_f32 v[136:137], v[88:89], v[198:199], v[136:137]
	v_pk_fma_f32 v[138:139], v[90:91], v[200:201], v[138:139]
	v_pk_fma_f32 v[140:141], v[92:93], v[202:203], v[140:141]
	v_pk_fma_f32 v[142:143], v[94:95], v[204:205], v[142:143]
	v_pk_fma_f32 v[144:145], v[88:89], v[248:249], v[144:145]
	v_pk_fma_f32 v[146:147], v[90:91], v[250:251], v[146:147]
	v_pk_fma_f32 v[148:149], v[92:93], v[252:253], v[148:149]
	v_pk_fma_f32 v[150:151], v[94:95], v[254:255], v[150:151]
	v_pk_fma_f32 v[152:153], v[88:89], v[240:241], v[152:153]
	v_pk_fma_f32 v[154:155], v[90:91], v[242:243], v[154:155]
	v_pk_fma_f32 v[156:157], v[92:93], v[244:245], v[156:157]
	v_pk_fma_f32 v[158:159], v[94:95], v[246:247], v[158:159]
	v_cvt_pk_bf16_f32 v164, v136, v137
	v_cvt_pk_bf16_f32 v165, v138, v139
	v_cvt_pk_bf16_f32 v166, v140, v141
	v_cvt_pk_bf16_f32 v167, v142, v143
	global_store_dwordx4 v161, v[164:167], s[44:45]
	s_add_u32 s44, s44, 0x1000
	s_addc_u32 s45, s45, 0
	s_nop 1
	v_lshlrev_b32_e32 v88, 16, v36
	v_and_b32_e32 v89, 0xffff0000, v36
	v_lshlrev_b32_e32 v90, 16, v37
	v_and_b32_e32 v91, 0xffff0000, v37
	v_lshlrev_b32_e32 v92, 16, v38
	v_and_b32_e32 v93, 0xffff0000, v38
	v_lshlrev_b32_e32 v94, 16, v39
	v_and_b32_e32 v95, 0xffff0000, v39
	v_pk_fma_f32 v[144:145], v[88:89], v[198:199], v[144:145]
	v_pk_fma_f32 v[146:147], v[90:91], v[200:201], v[146:147]
	v_pk_fma_f32 v[148:149], v[92:93], v[202:203], v[148:149]
	v_pk_fma_f32 v[150:151], v[94:95], v[204:205], v[150:151]
	v_pk_fma_f32 v[152:153], v[88:89], v[248:249], v[152:153]
	v_pk_fma_f32 v[154:155], v[90:91], v[250:251], v[154:155]
	v_pk_fma_f32 v[156:157], v[92:93], v[252:253], v[156:157]
	v_pk_fma_f32 v[158:159], v[94:95], v[254:255], v[158:159]
	v_cvt_pk_bf16_f32 v164, v144, v145
	v_cvt_pk_bf16_f32 v165, v146, v147
	v_cvt_pk_bf16_f32 v166, v148, v149
	v_cvt_pk_bf16_f32 v167, v150, v151
	global_store_dwordx4 v161, v[164:167], s[44:45]
	s_add_u32 s44, s44, 0x1000
	s_addc_u32 s45, s45, 0
	s_nop 1
	v_lshlrev_b32_e32 v88, 16, v40
	v_and_b32_e32 v89, 0xffff0000, v40
	v_lshlrev_b32_e32 v90, 16, v41
	v_and_b32_e32 v91, 0xffff0000, v41
	v_lshlrev_b32_e32 v92, 16, v42
	v_and_b32_e32 v93, 0xffff0000, v42
	v_lshlrev_b32_e32 v94, 16, v43
	v_and_b32_e32 v95, 0xffff0000, v43
	v_pk_fma_f32 v[152:153], v[88:89], v[198:199], v[152:153]
	v_pk_fma_f32 v[154:155], v[90:91], v[200:201], v[154:155]
	v_pk_fma_f32 v[156:157], v[92:93], v[202:203], v[156:157]
	v_pk_fma_f32 v[158:159], v[94:95], v[204:205], v[158:159]
	v_cvt_pk_bf16_f32 v164, v152, v153
	v_cvt_pk_bf16_f32 v165, v154, v155
	v_cvt_pk_bf16_f32 v166, v156, v157
	v_cvt_pk_bf16_f32 v167, v158, v159
	global_store_dwordx4 v161, v[164:167], s[44:45]
	s_add_u32 s44, s44, 0x1000
	s_addc_u32 s45, s45, 0
	s_nop 1
	s_add_u32 s28, s28, 0x1000000
	s_addc_u32 s29, s29, 0
	s_waitcnt vmcnt(8)
; DI u32x4 pack8(const float (&f)[8]) { u32x4 w; w.x = pk2(f[0], f[1]); w.y = pk2(f[2], f[3]); w.z = pk2(f[4], f[5]); w.w = pk2(f[6], f[7]); return w; }
; DI void phase_conv(const Params& p) {
;     ...
; #pragma unroll
;         for (int o = 0; o < 8; ++o) {
;             float acc[8];
; #pragma unroll
;             for (int e = 0; e < 8; ++e) acc[e] = bs[e];
; #pragma unroll
;             for (int jx = 0; jx < 4; ++jx) { float f[8]; unpack8(raw[o + jx], f);
; #pragma unroll
;                 for (int e = 0; e < 8; ++e) acc[e] += f[e] * wv[jx][e]; }
;             *(u32x4*)(xc + (size_t)(tok0 + o) * DM + ch) = pack8(acc);
;         }
	s_cmp_eq_u32 s40, 0
	s_cbranch_scc0 .Lcv_nopad3
	v_mov_b32_e32 v44, 0
	v_mov_b32_e32 v45, 0
	v_mov_b32_e32 v46, 0
	v_mov_b32_e32 v47, 0
	v_mov_b32_e32 v48, 0
	v_mov_b32_e32 v49, 0
	v_mov_b32_e32 v50, 0
	v_mov_b32_e32 v51, 0
	v_mov_b32_e32 v52, 0
	v_mov_b32_e32 v53, 0
	v_mov_b32_e32 v54, 0
	v_mov_b32_e32 v55, 0
.Lcv_nopad3:
	s_mov_b64 s[44:45], s[28:29]
	v_lshlrev_b32_e32 v88, 16, v44
	v_and_b32_e32 v89, 0xffff0000, v44
	v_lshlrev_b32_e32 v90, 16, v45
	v_and_b32_e32 v91, 0xffff0000, v45
	v_lshlrev_b32_e32 v92, 16, v46
	v_and_b32_e32 v93, 0xffff0000, v46
	v_lshlrev_b32_e32 v94, 16, v47
	v_and_b32_e32 v95, 0xffff0000, v47
	v_pk_fma_f32 v[96:97], v[88:89], v[232:233], v[206:207]
	v_pk_fma_f32 v[98:99], v[90:91], v[234:235], v[208:209]
	v_pk_fma_f32 v[100:101], v[92:93], v[236:237], v[210:211]
	v_pk_fma_f32 v[102:103], v[94:95], v[238:239], v[212:213]
	v_lshlrev_b32_e32 v88, 16, v48
	v_and_b32_e32 v89, 0xffff0000, v48
	v_lshlrev_b32_e32 v90, 16, v49
	v_and_b32_e32 v91, 0xffff0000, v49
	v_lshlrev_b32_e32 v92, 16, v50
	v_and_b32_e32 v93, 0xffff0000, v50
	v_lshlrev_b32_e32 v94, 16, v51
	v_and_b32_e32 v95, 0xffff0000, v51
	v_pk_fma_f32 v[96:97], v[88:89], v[240:241], v[96:97]
	v_pk_fma_f32 v[98:99], v[90:91], v[242:243], v[98:99]
	v_pk_fma_f32 v[100:101], v[92:93], v[244:245], v[100:101]
	v_pk_fma_f32 v[102:103], v[94:95], v[246:247], v[102:103]
	v_pk_fma_f32 v[104:105], v[88:89], v[232:233], v[206:207]
	v_pk_fma_f32 v[106:107], v[90:91], v[234:235], v[208:209]
	v_pk_fma_f32 v[108:109], v[92:93], v[236:237], v[210:211]
	v_pk_fma_f32 v[110:111], v[94:95], v[238:239], v[212:213]
	v_lshlrev_b32_e32 v88, 16, v52
	v_and_b32_e32 v89, 0xffff0000, v52
	v_lshlrev_b32_e32 v90, 16, v53
	v_and_b32_e32 v91, 0xffff0000, v53
	v_lshlrev_b32_e32 v92, 16, v54
	v_and_b32_e32 v93, 0xffff0000, v54
	v_lshlrev_b32_e32 v94, 16, v55
	v_and_b32_e32 v95, 0xffff0000, v55
	v_pk_fma_f32 v[96:97], v[88:89], v[248:249], v[96:97]
	v_pk_fma_f32 v[98:99], v[90:91], v[250:251], v[98:99]
	v_pk_fma_f32 v[100:101], v[92:93], v[252:253], v[100:101]
	v_pk_fma_f32 v[102:103], v[94:95], v[254:255], v[102:103]
	v_pk_fma_f32 v[104:105], v[88:89], v[240:241], v[104:105]
	v_pk_fma_f32 v[106:107], v[90:91], v[242:243], v[106:107]
	v_pk_fma_f32 v[108:109], v[92:93], v[244:245], v[108:109]
	v_pk_fma_f32 v[110:111], v[94:95], v[246:247], v[110:111]
	v_pk_fma_f32 v[112:113], v[88:89], v[232:233], v[206:207]
	v_pk_fma_f32 v[114:115], v[90:91], v[234:235], v[208:209]
	v_pk_fma_f32 v[116:117], v[92:93], v[236:237], v[210:211]
	v_pk_fma_f32 v[118:119], v[94:95], v[238:239], v[212:213]
	v_lshlrev_b32_e32 v88, 16, v56
	v_and_b32_e32 v89, 0xffff0000, v56
	v_lshlrev_b32_e32 v90, 16, v57
	v_and_b32_e32 v91, 0xffff0000, v57
	v_lshlrev_b32_e32 v92, 16, v58
	v_and_b32_e32 v93, 0xffff0000, v58
	v_lshlrev_b32_e32 v94, 16, v59
	v_and_b32_e32 v95, 0xffff0000, v59
	v_pk_fma_f32 v[96:97], v[88:89], v[198:199], v[96:97]
	v_pk_fma_f32 v[98:99], v[90:91], v[200:201], v[98:99]
	v_pk_fma_f32 v[100:101], v[92:93], v[202:203], v[100:101]
	v_pk_fma_f32 v[102:103], v[94:95], v[204:205], v[102:103]
	v_pk_fma_f32 v[104:105], v[88:89], v[248:249], v[104:105]
	v_pk_fma_f32 v[106:107], v[90:91], v[250:251], v[106:107]
	v_pk_fma_f32 v[108:109], v[92:93], v[252:253], v[108:109]
	v_pk_fma_f32 v[110:111], v[94:95], v[254:255], v[110:111]
	v_pk_fma_f32 v[112:113], v[88:89], v[240:241], v[112:113]
	v_pk_fma_f32 v[114:115], v[90:91], v[242:243], v[114:115]
	v_pk_fma_f32 v[116:117], v[92:93], v[244:245], v[116:117]
	v_pk_fma_f32 v[118:119], v[94:95], v[246:247], v[118:119]
	v_pk_fma_f32 v[120:121], v[88:89], v[232:233], v[206:207]
	v_pk_fma_f32 v[122:123], v[90:91], v[234:235], v[208:209]
	v_pk_fma_f32 v[124:125], v[92:93], v[236:237], v[210:211]
	v_pk_fma_f32 v[126:127], v[94:95], v[238:239], v[212:213]
	v_cvt_pk_bf16_f32 v164, v96, v97
	v_cvt_pk_bf16_f32 v165, v98, v99
	v_cvt_pk_bf16_f32 v166, v100, v101
	v_cvt_pk_bf16_f32 v167, v102, v103
	global_store_dwordx4 v161, v[164:167], s[44:45]
	s_add_u32 s44, s44, 0x1000
	s_addc_u32 s45, s45, 0
	s_nop 1
	v_lshlrev_b32_e32 v88, 16, v60
	v_and_b32_e32 v89, 0xffff0000, v60
	v_lshlrev_b32_e32 v90, 16, v61
	v_and_b32_e32 v91, 0xffff0000, v61
	v_lshlrev_b32_e32 v92, 16, v62
	v_and_b32_e32 v93, 0xffff0000, v62
	v_lshlrev_b32_e32 v94, 16, v63
	v_and_b32_e32 v95, 0xffff0000, v63
	v_pk_fma_f32 v[104:105], v[88:89], v[198:199], v[104:105]
	v_pk_fma_f32 v[106:107], v[90:91], v[200:201], v[106:107]
	v_pk_fma_f32 v[108:109], v[92:93], v[202:203], v[108:109]
	v_pk_fma_f32 v[110:111], v[94:95], v[204:205], v[110:111]
	v_pk_fma_f32 v[112:113], v[88:89], v[248:249], v[112:113]
	v_pk_fma_f32 v[114:115], v[90:91], v[250:251], v[114:115]
	v_pk_fma_f32 v[116:117], v[92:93], v[252:253], v[116:117]
	v_pk_fma_f32 v[118:119], v[94:95], v[254:255], v[118:119]
	v_pk_fma_f32 v[120:121], v[88:89], v[240:241], v[120:121]
	v_pk_fma_f32 v[122:123], v[90:91], v[242:243], v[122:123]
	v_pk_fma_f32 v[124:125], v[92:93], v[244:245], v[124:125]
	v_pk_fma_f32 v[126:127], v[94:95], v[246:247], v[126:127]
	v_pk_fma_f32 v[128:129], v[88:89], v[232:233], v[206:207]
	v_pk_fma_f32 v[130:131], v[90:91], v[234:235], v[208:209]
	v_pk_fma_f32 v[132:133], v[92:93], v[236:237], v[210:211]
	v_pk_fma_f32 v[134:135], v[94:95], v[238:239], v[212:213]
	v_cvt_pk_bf16_f32 v164, v104, v105
	v_cvt_pk_bf16_f32 v165, v106, v107
	v_cvt_pk_bf16_f32 v166, v108, v109
	v_cvt_pk_bf16_f32 v167, v110, v111
	global_store_dwordx4 v161, v[164:167], s[44:45]
	s_add_u32 s44, s44, 0x1000
	s_addc_u32 s45, s45, 0
	s_nop 1
	v_lshlrev_b32_e32 v88, 16, v64
	v_and_b32_e32 v89, 0xffff0000, v64
	v_lshlrev_b32_e32 v90, 16, v65
	v_and_b32_e32 v91, 0xffff0000, v65
; DI u32x4 pack8(const float (&f)[8]) { u32x4 w; w.x = pk2(f[0], f[1]); w.y = pk2(f[2], f[3]); w.z = pk2(f[4], f[5]); w.w = pk2(f[6], f[7]); return w; }
; DI void phase_conv(const Params& p) {
;     ...
; #pragma unroll
;         for (int o = 0; o < 8; ++o) {
;             float acc[8];
; #pragma unroll
;             for (int e = 0; e < 8; ++e) acc[e] = bs[e];
; #pragma unroll
;             for (int jx = 0; jx < 4; ++jx) { float f[8]; unpack8(raw[o + jx], f);
; #pragma unroll
;                 for (int e = 0; e < 8; ++e) acc[e] += f[e] * wv[jx][e]; }
;             *(u32x4*)(xc + (size_t)(tok0 + o) * DM + ch) = pack8(acc);
;         }
	v_lshlrev_b32_e32 v92, 16, v66
	v_and_b32_e32 v93, 0xffff0000, v66
	v_lshlrev_b32_e32 v94, 16, v67
	v_and_b32_e32 v95, 0xffff0000, v67
	v_pk_fma_f32 v[112:113], v[88:89], v[198:199], v[112:113]
	v_pk_fma_f32 v[114:115], v[90:91], v[200:201], v[114:115]
	v_pk_fma_f32 v[116:117], v[92:93], v[202:203], v[116:117]
	v_pk_fma_f32 v[118:119], v[94:95], v[204:205], v[118:119]
	v_pk_fma_f32 v[120:121], v[88:89], v[248:249], v[120:121]
	v_pk_fma_f32 v[122:123], v[90:91], v[250:251], v[122:123]
	v_pk_fma_f32 v[124:125], v[92:93], v[252:253], v[124:125]
	v_pk_fma_f32 v[126:127], v[94:95], v[254:255], v[126:127]
	v_pk_fma_f32 v[128:129], v[88:89], v[240:241], v[128:129]
	v_pk_fma_f32 v[130:131], v[90:91], v[242:243], v[130:131]
	v_pk_fma_f32 v[132:133], v[92:93], v[244:245], v[132:133]
	v_pk_fma_f32 v[134:135], v[94:95], v[246:247], v[134:135]
	v_pk_fma_f32 v[136:137], v[88:89], v[232:233], v[206:207]
	v_pk_fma_f32 v[138:139], v[90:91], v[234:235], v[208:209]
	v_pk_fma_f32 v[140:141], v[92:93], v[236:237], v[210:211]
	v_pk_fma_f32 v[142:143], v[94:95], v[238:239], v[212:213]
	v_cvt_pk_bf16_f32 v164, v112, v113
	v_cvt_pk_bf16_f32 v165, v114, v115
	v_cvt_pk_bf16_f32 v166, v116, v117
	v_cvt_pk_bf16_f32 v167, v118, v119
	global_store_dwordx4 v161, v[164:167], s[44:45]
	s_add_u32 s44, s44, 0x1000
	s_addc_u32 s45, s45, 0
	s_nop 1
	v_lshlrev_b32_e32 v88, 16, v68
	v_and_b32_e32 v89, 0xffff0000, v68
	v_lshlrev_b32_e32 v90, 16, v69
	v_and_b32_e32 v91, 0xffff0000, v69
	v_lshlrev_b32_e32 v92, 16, v70
	v_and_b32_e32 v93, 0xffff0000, v70
	v_lshlrev_b32_e32 v94, 16, v71
	v_and_b32_e32 v95, 0xffff0000, v71
	v_pk_fma_f32 v[120:121], v[88:89], v[198:199], v[120:121]
	v_pk_fma_f32 v[122:123], v[90:91], v[200:201], v[122:123]
	v_pk_fma_f32 v[124:125], v[92:93], v[202:203], v[124:125]
	v_pk_fma_f32 v[126:127], v[94:95], v[204:205], v[126:127]
	v_pk_fma_f32 v[128:129], v[88:89], v[248:249], v[128:129]
	v_pk_fma_f32 v[130:131], v[90:91], v[250:251], v[130:131]
	v_pk_fma_f32 v[132:133], v[92:93], v[252:253], v[132:133]
	v_pk_fma_f32 v[134:135], v[94:95], v[254:255], v[134:135]
	v_pk_fma_f32 v[136:137], v[88:89], v[240:241], v[136:137]
	v_pk_fma_f32 v[138:139], v[90:91], v[242:243], v[138:139]
	v_pk_fma_f32 v[140:141], v[92:93], v[244:245], v[140:141]
	v_pk_fma_f32 v[142:143], v[94:95], v[246:247], v[142:143]
	v_pk_fma_f32 v[144:145], v[88:89], v[232:233], v[206:207]
	v_pk_fma_f32 v[146:147], v[90:91], v[234:235], v[208:209]
	v_pk_fma_f32 v[148:149], v[92:93], v[236:237], v[210:211]
	v_pk_fma_f32 v[150:151], v[94:95], v[238:239], v[212:213]
	v_cvt_pk_bf16_f32 v164, v120, v121
	v_cvt_pk_bf16_f32 v165, v122, v123
	v_cvt_pk_bf16_f32 v166, v124, v125
	v_cvt_pk_bf16_f32 v167, v126, v127
	global_store_dwordx4 v161, v[164:167], s[44:45]
	s_add_u32 s44, s44, 0x1000
	s_addc_u32 s45, s45, 0
	s_nop 1
	v_lshlrev_b32_e32 v88, 16, v72
	v_and_b32_e32 v89, 0xffff0000, v72
	v_lshlrev_b32_e32 v90, 16, v73
	v_and_b32_e32 v91, 0xffff0000, v73
	v_lshlrev_b32_e32 v92, 16, v74
	v_and_b32_e32 v93, 0xffff0000, v74
	v_lshlrev_b32_e32 v94, 16, v75
	v_and_b32_e32 v95, 0xffff0000, v75
	v_pk_fma_f32 v[128:129], v[88:89], v[198:199], v[128:129]
	v_pk_fma_f32 v[130:131], v[90:91], v[200:201], v[130:131]
	v_pk_fma_f32 v[132:133], v[92:93], v[202:203], v[132:133]
	v_pk_fma_f32 v[134:135], v[94:95], v[204:205], v[134:135]
	v_pk_fma_f32 v[136:137], v[88:89], v[248:249], v[136:137]
	v_pk_fma_f32 v[138:139], v[90:91], v[250:251], v[138:139]
	v_pk_fma_f32 v[140:141], v[92:93], v[252:253], v[140:141]
	v_pk_fma_f32 v[142:143], v[94:95], v[254:255], v[142:143]
	v_pk_fma_f32 v[144:145], v[88:89], v[240:241], v[144:145]
	v_pk_fma_f32 v[146:147], v[90:91], v[242:243], v[146:147]
	v_pk_fma_f32 v[148:149], v[92:93], v[244:245], v[148:149]
	v_pk_fma_f32 v[150:151], v[94:95], v[246:247], v[150:151]
	v_pk_fma_f32 v[152:153], v[88:89], v[232:233], v[206:207]
	v_pk_fma_f32 v[154:155], v[90:91], v[234:235], v[208:209]
	v_pk_fma_f32 v[156:157], v[92:93], v[236:237], v[210:211]
	v_pk_fma_f32 v[158:159], v[94:95], v[238:239], v[212:213]
; DI int otid() { int t = threadIdx.x; asm volatile("" : "+v"(t)); return t; }
; DI u32x4 pack8(const float (&f)[8]) { u32x4 w; w.x = pk2(f[0], f[1]); w.y = pk2(f[2], f[3]); w.z = pk2(f[4], f[5]); w.w = pk2(f[6], f[7]); return w; }
; DI void phase_conv(const Params& p) {
;     ...
;     for (size_t idx = (size_t)blockIdx.x * 512 + otid(); idx < (size_t)(MTOK / 8) * 256; idx += (size_t)gridDim.x * 512) {
;         const int tok0 = (int)(idx >> 8) * 8, ch = (int)(idx & 255) * 8, t0 = tok0 & (SEQ - 1);
;         float wv[4][8], bs[8];
;         { const f32x4 b0 = *(const f32x4*)(p.in[15] + ch), b1 = *(const f32x4*)(p.in[15] + ch + 4);
; #pragma unroll
;           for (int e = 0; e < 4; ++e) { bs[e] = b0[e]; bs[4 + e] = b1[e]; } }
; #pragma unroll
;         for (int jx = 0; jx < 4; ++jx) { const f32x4 w0 = *(const f32x4*)(p.in[14] + jx * 2048 + ch), w1 = *(const f32x4*)(p.in[14] + jx * 2048 + ch + 4);
; #pragma unroll
;             for (int e = 0; e < 4; ++e) { wv[jx][e] = w0[e]; wv[jx][4 + e] = w1[e]; } }
;         u32x4 raw[11];
; #pragma unroll
;         for (int r = 0; r < 11; ++r) raw[r] = (r >= 3 || t0 > 0) ? *(const u32x4*)(big + (size_t)(tok0 - 3 + r) * 4096 + ch) : (u32x4){0u, 0u, 0u, 0u};
; #pragma unroll
;         for (int o = 0; o < 8; ++o) {
;             float acc[8];
; #pragma unroll
;             for (int e = 0; e < 8; ++e) acc[e] = bs[e];
; #pragma unroll
;             for (int jx = 0; jx < 4; ++jx) { float f[8]; unpack8(raw[o + jx], f);
; #pragma unroll
;                 for (int e = 0; e < 8; ++e) acc[e] += f[e] * wv[jx][e]; }
;             *(u32x4*)(xc + (size_t)(tok0 + o) * DM + ch) = pack8(acc);
;         }
	v_cvt_pk_bf16_f32 v164, v128, v129
	v_cvt_pk_bf16_f32 v165, v130, v131
	v_cvt_pk_bf16_f32 v166, v132, v133
	v_cvt_pk_bf16_f32 v167, v134, v135
	global_store_dwordx4 v161, v[164:167], s[44:45]
	s_add_u32 s44, s44, 0x1000
	s_addc_u32 s45, s45, 0
	s_nop 1
	v_lshlrev_b32_e32 v88, 16, v76
	v_and_b32_e32 v89, 0xffff0000, v76
	v_lshlrev_b32_e32 v90, 16, v77
	v_and_b32_e32 v91, 0xffff0000, v77
	v_lshlrev_b32_e32 v92, 16, v78
	v_and_b32_e32 v93, 0xffff0000, v78
	v_lshlrev_b32_e32 v94, 16, v79
	v_and_b32_e32 v95, 0xffff0000, v79
	v_pk_fma_f32 v[136:137], v[88:89], v[198:199], v[136:137]
	v_pk_fma_f32 v[138:139], v[90:91], v[200:201], v[138:139]
	v_pk_fma_f32 v[140:141], v[92:93], v[202:203], v[140:141]
	v_pk_fma_f32 v[142:143], v[94:95], v[204:205], v[142:143]
	v_pk_fma_f32 v[144:145], v[88:89], v[248:249], v[144:145]
	v_pk_fma_f32 v[146:147], v[90:91], v[250:251], v[146:147]
	v_pk_fma_f32 v[148:149], v[92:93], v[252:253], v[148:149]
	v_pk_fma_f32 v[150:151], v[94:95], v[254:255], v[150:151]
	v_pk_fma_f32 v[152:153], v[88:89], v[240:241], v[152:153]
	v_pk_fma_f32 v[154:155], v[90:91], v[242:243], v[154:155]
	v_pk_fma_f32 v[156:157], v[92:93], v[244:245], v[156:157]
	v_pk_fma_f32 v[158:159], v[94:95], v[246:247], v[158:159]
	v_cvt_pk_bf16_f32 v164, v136, v137
	v_cvt_pk_bf16_f32 v165, v138, v139
	v_cvt_pk_bf16_f32 v166, v140, v141
	v_cvt_pk_bf16_f32 v167, v142, v143
	global_store_dwordx4 v161, v[164:167], s[44:45]
	s_add_u32 s44, s44, 0x1000
	s_addc_u32 s45, s45, 0
	s_nop 1
	v_lshlrev_b32_e32 v88, 16, v80
	v_and_b32_e32 v89, 0xffff0000, v80
	v_lshlrev_b32_e32 v90, 16, v81
	v_and_b32_e32 v91, 0xffff0000, v81
	v_lshlrev_b32_e32 v92, 16, v82
	v_and_b32_e32 v93, 0xffff0000, v82
	v_lshlrev_b32_e32 v94, 16, v83
	v_and_b32_e32 v95, 0xffff0000, v83
	v_pk_fma_f32 v[144:145], v[88:89], v[198:199], v[144:145]
	v_pk_fma_f32 v[146:147], v[90:91], v[200:201], v[146:147]
	v_pk_fma_f32 v[148:149], v[92:93], v[202:203], v[148:149]
	v_pk_fma_f32 v[150:151], v[94:95], v[204:205], v[150:151]
	v_pk_fma_f32 v[152:153], v[88:89], v[248:249], v[152:153]
	v_pk_fma_f32 v[154:155], v[90:91], v[250:251], v[154:155]
	v_pk_fma_f32 v[156:157], v[92:93], v[252:253], v[156:157]
	v_pk_fma_f32 v[158:159], v[94:95], v[254:255], v[158:159]
	v_cvt_pk_bf16_f32 v164, v144, v145
	v_cvt_pk_bf16_f32 v165, v146, v147
	v_cvt_pk_bf16_f32 v166, v148, v149
	v_cvt_pk_bf16_f32 v167, v150, v151
	global_store_dwordx4 v161, v[164:167], s[44:45]
	s_add_u32 s44, s44, 0x1000
	s_addc_u32 s45, s45, 0
	s_nop 1
	v_lshlrev_b32_e32 v88, 16, v84
	v_and_b32_e32 v89, 0xffff0000, v84
	v_lshlrev_b32_e32 v90, 16, v85
	v_and_b32_e32 v91, 0xffff0000, v85
	v_lshlrev_b32_e32 v92, 16, v86
	v_and_b32_e32 v93, 0xffff0000, v86
	v_lshlrev_b32_e32 v94, 16, v87
	v_and_b32_e32 v95, 0xffff0000, v87
	v_pk_fma_f32 v[152:153], v[88:89], v[198:199], v[152:153]
	v_pk_fma_f32 v[154:155], v[90:91], v[200:201], v[154:155]
	v_pk_fma_f32 v[156:157], v[92:93], v[202:203], v[156:157]
	v_pk_fma_f32 v[158:159], v[94:95], v[204:205], v[158:159]
	v_cvt_pk_bf16_f32 v164, v152, v153
	v_cvt_pk_bf16_f32 v165, v154, v155
	v_cvt_pk_bf16_f32 v166, v156, v157
	v_cvt_pk_bf16_f32 v167, v158, v159
	global_store_dwordx4 v161, v[164:167], s[44:45]
	s_add_u32 s44, s44, 0x1000
	s_addc_u32 s45, s45, 0
	s_nop 1
	s_add_u32 s28, s28, 0x1000000
	s_addc_u32 s29, s29, 0
	s_branch .LBB0_884
.Lcv_orig:
	s_load_dwordx2 s[8:9], s[0:1], 0xf0
	s_load_dwordx4 s[12:15], s[0:1], 0x70
	s_mov_b32 s30, s18
	s_mov_b32 s31, s3
	s_mov_b64 s[34:35], 0
	s_waitcnt lgkmcnt(0)
	s_add_u32 s24, s8, 0xbf00000
	s_addc_u32 s25, s9, 0
	s_add_u32 s26, s8, 0x7f00000
	s_addc_u32 s27, s9, 0
	s_lshl_b64 s[8:9], s[2:3], 12
	s_lshl_b64 s[28:29], s[30:31], 9
	v_lshl_add_u64 v[56:57], v[0:1], 3, s[8:9]
	s_lshl_b64 s[30:31], s[30:31], 12
	v_mov_b32_e32 v59, 0
	s_mov_b64 s[36:37], 0x2000
	s_movk_i32 s3, 0x2000
	s_mov_b64 s[38:39], 0x4000
	s_movk_i32 s46, 0x4000
	s_mov_b64 s[40:41], 0x6000
	s_movk_i32 s47, 0x6000
	s_mov_b32 s48, 0x8000
	s_mov_b32 s49, 0xa000
	s_mov_b32 s50, 0xc000
	s_mov_b64 s[42:43], 0x7ffff
	s_branch .LBB0_878
